# hand-written rwkv scan (LDS-prefetched, 3-buffer) + GEMM_IN with LDS-DMA BK=64 swizzled
# speedup vs baseline: 1.0745x; 1.0745x over previous
.LBB0_130:
	s_andn2_b64 vcc, exec, s[0:1]
	s_cbranch_vccnz .LBB0_138
	s_mov_b32 s68, s25
	s_mov_b32 s69, 0
.Lscan_ctx_again:
	s_add_i32 s0, s25, 0xffffff80
	s_lshr_b32 s29, s0, 6
	s_and_b32 s88, s0, 63
	s_lshl_b32 s26, s29, 8
	s_movk_i32 s27, 0x100
	s_mov_b32 s28, 1
	s_setprio 1
	s_branch .Lscan_common

.Lscan_sample_again:
	s_lshr_b32 s29, s25, 6
	s_and_b32 s88, s25, 63
	s_lshl_b32 s26, s29, 11
	s_addk_i32 s26, 0x1000
	s_movk_i32 s27, 0x800
	s_mov_b32 s28, 0
	s_setprio 3
.Lscan_common:
	s_lshr_b32 s0, s88, 3
	s_bfe_u32 s1, s88, 0x10002
	s_and_b32 s88, s88, 3
	v_and_b32_e32 v36, 15, v128
	v_lshrrev_b32_e32 v37, 4, v128
	s_lshr_b32 s5, s27, 4
	s_mov_b32 s90, 0x8000
	s_cmp_eq_u32 s1, 0
	s_cselect_b32 s90, s90, 0xffff8000
	v_lshlrev_b32_e32 v24, 4, v36
	v_lshlrev_b32_e32 v25, 2, v37
	v_add_u32_e32 v25, 0x500, v25
	v_mov_b32_e32 v38, 0x540
	v_mul_u32_u24_e32 v38, v37, v38
	v_add_u32_e32 v26, v38, v24
	v_lshl_add_u32 v27, v36, 2, v38
	v_add_u32_e32 v27, 0x500, v27
	s_add_i32 s92, s26, s27
	s_add_i32 s92, s92, -1
	v_sub_u32_e32 v38, s92, v37
	v_add_u32_e32 v39, s26, v37
	s_cmp_eq_u32 s1, 0
	s_cselect_b64 vcc, -1, 0
	v_cndmask_b32_e32 v38, v38, v39, vcc
	v_lshlrev_b32_e32 v38, 11, v38
	s_lshl_b32 s92, s0, 8
	v_add_u32_e32 v38, s92, v38
	v_add_u32_e32 v39, v38, v24
	s_lshl_b32 s1, s1, 24
	s_add_u32 s92, s1, 0x176a6100
	v_add_u32_e32 v28, s92, v39
	s_mov_b32 s92, 0x156a6100
	v_add_u32_e32 v29, s92, v39
	s_add_u32 s92, s1, 0x196a6100
	v_add_u32_e32 v30, s92, v39
	s_add_u32 s92, s1, 0x1b6a6100
	v_add_u32_e32 v31, s92, v39
	s_mov_b32 s92, 0x146a6100
	v_add_u32_e32 v32, s92, v39
	s_lshl_b32 s92, s88, 6
	s_add_u32 s92, s92, 0x166a6100
	v_lshl_add_u32 v33, v36, 2, v38
	v_add_u32_e32 v33, s92, v33
	s_add_i32 s92, s26, s27
	s_add_i32 s92, s92, -1
	v_sub_u32_e32 v38, s92, v36
	v_add_u32_e32 v39, s26, v36
	v_cndmask_b32_e32 v38, v38, v39, vcc
	v_lshlrev_b32_e32 v38, 11, v38
	s_lshl_b32 s92, s0, 8
	s_lshl_b32 s26, s88, 6
	s_add_u32 s92, s92, s26
	s_add_u32 s92, s92, s1
	s_add_u32 s92, s92, 0x1d6a6100
	v_lshl_add_u32 v38, v37, 2, v38
	v_add_u32_e32 v34, s92, v38
	v_mov_b32_e32 v138, v34
	s_mov_b32 s4, 0
	s_mul_i32 s92, s4, s90
	v_add_u32_e32 v132, s92, v28
	v_add_u32_e32 v133, s92, v29
	v_add_u32_e32 v134, s92, v30
	v_add_u32_e32 v135, s92, v31
	v_add_u32_e32 v136, s92, v32
	v_add_u32_e32 v137, s92, v33
	global_load_dwordx4 v[146:149], v132, s[96:97]
	global_load_dwordx4 v[150:153], v133, s[96:97]
	global_load_dwordx4 v[154:157], v134, s[96:97]
	global_load_dwordx4 v[158:161], v135, s[96:97]
	global_load_dwordx4 v[162:165], v136, s[96:97]
	global_load_dword v166, v137, s[96:97]
	v_readlane_b32 s92, v255, 44
	s_lshl_b32 s29, s29, 2
	s_add_i32 s29, s29, s92
	s_lshl_b32 s29, s29, 1
	s_lshr_b32 s1, s1, 24
	s_add_i32 s29, s29, s1
	s_lshl_b32 s29, s29, 3
	s_add_i32 s29, s29, s0
	s_lshl_b32 s29, s29, 14
	s_lshl_b32 s92, s88, 12
	s_add_i32 s29, s29, s92
	v_lshl_add_u32 v39, v37, 8, v24
	v_add_u32_e32 v39, s29, v39
	v_mov_b32_e32 v0, 0
	v_mov_b32_e32 v1, 0
	v_mov_b32_e32 v2, 0
	v_mov_b32_e32 v3, 0
	s_cmp_lg_u32 s28, 0
	s_cbranch_scc1 .Lscan_nostate
	global_load_dwordx4 v[0:3], v39, s[80:81]
.Lscan_nostate:
	v_cmp_eq_u32_e64 s[36:37], 0, v36
	v_cmp_eq_u32_e64 s[38:39], 1, v36
	v_cmp_eq_u32_e64 s[40:41], 2, v36
	v_cmp_eq_u32_e64 s[42:43], 3, v36
	v_cmp_eq_u32_e64 s[44:45], 4, v36
	v_cmp_eq_u32_e64 s[46:47], 5, v36
	v_cmp_eq_u32_e64 s[48:49], 6, v36
	v_cmp_eq_u32_e64 s[50:51], 7, v36
	v_cmp_eq_u32_e64 s[52:53], 8, v36
	v_cmp_eq_u32_e64 s[54:55], 9, v36
	v_cmp_eq_u32_e64 s[56:57], 10, v36
	v_cmp_eq_u32_e64 s[58:59], 11, v36
	v_cmp_eq_u32_e64 s[60:61], 12, v36
	v_cmp_eq_u32_e64 s[62:63], 13, v36
	v_cmp_eq_u32_e64 s[64:65], 14, v36
	v_cmp_eq_u32_e64 s[66:67], 15, v36
	v_mov_b32_e32 v23, 0
	s_mov_b32 s6, 0
	s_mov_b32 s7, 21504
	s_mov_b32 s25, 43040
	v_mov_b32_e32 v139, v24
	v_mov_b32_e32 v140, v25
	v_add_u32_e32 v141, s7, v24
	v_add_u32_e32 v142, s7, v25
	v_add_u32_e32 v143, s7, v26
	v_add_u32_e32 v35, s7, v27
	s_cmp_lg_u32 s28, 0
	s_cbranch_scc1 .Lscan_w0
	s_waitcnt vmcnt(1)
	s_branch .Lscan_w1

.Lscan_w1:
	ds_write_b128 v26, v[146:149]
	ds_write_b128 v26, v[150:153] offset:256
	ds_write_b128 v26, v[154:157] offset:512
	ds_write_b128 v26, v[158:161] offset:768
	ds_write_b128 v26, v[162:165] offset:1024
	ds_write_b32 v27, v166
	s_add_i32 s0, s5, -1
	s_min_u32 s0, s0, 1
	s_mul_i32 s92, s0, s90
	v_add_u32_e32 v132, s92, v28
	v_add_u32_e32 v133, s92, v29
	v_add_u32_e32 v134, s92, v30
	v_add_u32_e32 v135, s92, v31
	v_add_u32_e32 v136, s92, v32
	v_add_u32_e32 v137, s92, v33
	s_waitcnt lgkmcnt(0)
	global_load_dwordx4 v[146:149], v132, s[96:97]
	global_load_dwordx4 v[150:153], v133, s[96:97]
	global_load_dwordx4 v[154:157], v134, s[96:97]
	global_load_dwordx4 v[158:161], v135, s[96:97]
	global_load_dwordx4 v[162:165], v136, s[96:97]
	global_load_dword v166, v137, s[96:97]
	s_barrier
	ds_read_b128 v[52:55], v139 offset:768
	ds_read_b32 v60, v140 offset:0
	ds_read_b128 v[44:47], v139 offset:256
	ds_read_b128 v[40:43], v139 offset:0
	ds_read_b128 v[48:51], v139 offset:512
	ds_read_b128 v[56:59], v139 offset:1024
	ds_read_b128 v[74:77], v139 offset:2112
	ds_read_b32 v82, v140 offset:1344
	ds_read_b128 v[66:69], v139 offset:1600
	ds_read_b128 v[62:65], v139 offset:1344
	ds_read_b128 v[70:73], v139 offset:1856
	ds_read_b128 v[78:81], v139 offset:2368
	s_waitcnt vmcnt(6)
	s_waitcnt lgkmcnt(6)
	v_mul_f32_e32 v8, v60, v52
	v_mul_f32_e32 v9, v60, v53
	v_mul_f32_e32 v10, v60, v54
	v_mul_f32_e32 v11, v60, v55
.Lscan_chunk:
	v_pk_mul_f32 v[16:17], v[0:1], v[44:45]
	v_pk_mul_f32 v[20:21], v[0:1], v[122:123]
	ds_read_b128 v[96:99], v139 offset:3456
	v_pk_fma_f32 v[16:17], v[2:3], v[46:47], v[16:17]
	v_pk_fma_f32 v[20:21], v[2:3], v[124:125], v[20:21]
	ds_read_b32 v104, v140 offset:2688
	v_add_f32_e32 v18, v16, v17
	v_add_f32_e32 v22, v20, v21
	v_pk_fma_f32 v[4:5], v[0:1], v[40:41], v[8:9]
	v_add_f32_dpp v18, v18, v18 quad_perm:[1,0,3,2] row_mask:0xf bank_mask:0xf bound_ctrl:1
	v_add_f32_dpp v22, v22, v22 quad_perm:[1,0,3,2] row_mask:0xf bank_mask:0xf bound_ctrl:1
	v_pk_fma_f32 v[6:7], v[2:3], v[42:43], v[10:11]
	v_add_f32_dpp v18, v18, v18 quad_perm:[2,3,0,1] row_mask:0xf bank_mask:0xf bound_ctrl:1
	v_add_f32_dpp v22, v22, v22 quad_perm:[2,3,0,1] row_mask:0xf bank_mask:0xf bound_ctrl:1
	ds_read_b128 v[88:91], v139 offset:2944
	v_add_f32_dpp v18, v18, v18 row_half_mirror row_mask:0xf bank_mask:0xf bound_ctrl:1
	v_add_f32_dpp v22, v22, v22 row_half_mirror row_mask:0xf bank_mask:0xf bound_ctrl:1
	ds_read_b128 v[84:87], v139 offset:2688
	v_add_f32_dpp v18, v18, v18 row_ror:8 row_mask:0xf bank_mask:0xf bound_ctrl:1
	v_add_f32_dpp v22, v22, v22 row_ror:8 row_mask:0xf bank_mask:0xf bound_ctrl:1
	ds_read_b128 v[92:95], v139 offset:3200
	v_pk_fma_f32 v[0:1], v[48:49], v[18:19], v[4:5] op_sel_hi:[1,0,1] neg_lo:[1,0,0] neg_hi:[1,0,0]
	v_pk_fma_f32 v[2:3], v[50:51], v[18:19], v[6:7] op_sel_hi:[1,0,1] neg_lo:[1,0,0] neg_hi:[1,0,0]
	v_cndmask_b32_e64 v23, v23, v22, s[66:67]
	ds_read_b128 v[100:103], v139 offset:3712
	s_waitcnt lgkmcnt(7)
	v_pk_mul_f32 v[8:9], v[74:75], v[82:83] op_sel_hi:[1,0]
	v_pk_mul_f32 v[10:11], v[76:77], v[82:83] op_sel_hi:[1,0]
	s_cmp_eq_u32 s4, 0
	s_cbranch_scc1 .Lscan_noy
	global_store_dword v138, v23, s[96:97]
	v_add_u32_e32 v138, s90, v138
.Lscan_noy:
	v_pk_mul_f32 v[16:17], v[0:1], v[66:67]
	v_pk_mul_f32 v[20:21], v[0:1], v[56:57]
	ds_read_b128 v[118:121], v139 offset:4800
	v_pk_fma_f32 v[16:17], v[2:3], v[68:69], v[16:17]
	v_pk_fma_f32 v[20:21], v[2:3], v[58:59], v[20:21]
	ds_read_b32 v126, v140 offset:4032
	v_add_f32_e32 v18, v16, v17
	v_add_f32_e32 v22, v20, v21
	v_pk_fma_f32 v[4:5], v[0:1], v[62:63], v[8:9]
	v_add_f32_dpp v18, v18, v18 quad_perm:[1,0,3,2] row_mask:0xf bank_mask:0xf bound_ctrl:1
	v_add_f32_dpp v22, v22, v22 quad_perm:[1,0,3,2] row_mask:0xf bank_mask:0xf bound_ctrl:1
	v_pk_fma_f32 v[6:7], v[2:3], v[64:65], v[10:11]
	v_add_f32_dpp v18, v18, v18 quad_perm:[2,3,0,1] row_mask:0xf bank_mask:0xf bound_ctrl:1
	v_add_f32_dpp v22, v22, v22 quad_perm:[2,3,0,1] row_mask:0xf bank_mask:0xf bound_ctrl:1
	ds_read_b128 v[110:113], v139 offset:4288
	v_add_f32_dpp v18, v18, v18 row_half_mirror row_mask:0xf bank_mask:0xf bound_ctrl:1
	v_add_f32_dpp v22, v22, v22 row_half_mirror row_mask:0xf bank_mask:0xf bound_ctrl:1
	ds_read_b128 v[106:109], v139 offset:4032
	v_add_f32_dpp v18, v18, v18 row_ror:8 row_mask:0xf bank_mask:0xf bound_ctrl:1
	v_add_f32_dpp v22, v22, v22 row_ror:8 row_mask:0xf bank_mask:0xf bound_ctrl:1
	ds_read_b128 v[114:117], v139 offset:4544
	v_pk_fma_f32 v[0:1], v[70:71], v[18:19], v[4:5] op_sel_hi:[1,0,1] neg_lo:[1,0,0] neg_hi:[1,0,0]
	v_pk_fma_f32 v[2:3], v[72:73], v[18:19], v[6:7] op_sel_hi:[1,0,1] neg_lo:[1,0,0] neg_hi:[1,0,0]
	v_cndmask_b32_e64 v23, v23, v22, s[36:37]
	ds_read_b128 v[122:125], v139 offset:5056
	s_waitcnt lgkmcnt(7)
	v_pk_mul_f32 v[8:9], v[96:97], v[104:105] op_sel_hi:[1,0]
	v_pk_mul_f32 v[10:11], v[98:99], v[104:105] op_sel_hi:[1,0]
	v_pk_mul_f32 v[16:17], v[0:1], v[88:89]
	v_pk_mul_f32 v[20:21], v[0:1], v[78:79]
	ds_read_b128 v[52:55], v139 offset:6144
	v_pk_fma_f32 v[16:17], v[2:3], v[90:91], v[16:17]
	v_pk_fma_f32 v[20:21], v[2:3], v[80:81], v[20:21]
	ds_read_b32 v60, v140 offset:5376
	v_add_f32_e32 v18, v16, v17
	v_add_f32_e32 v22, v20, v21
	v_pk_fma_f32 v[4:5], v[0:1], v[84:85], v[8:9]
	v_add_f32_dpp v18, v18, v18 quad_perm:[1,0,3,2] row_mask:0xf bank_mask:0xf bound_ctrl:1
	v_add_f32_dpp v22, v22, v22 quad_perm:[1,0,3,2] row_mask:0xf bank_mask:0xf bound_ctrl:1
	v_pk_fma_f32 v[6:7], v[2:3], v[86:87], v[10:11]
	v_add_f32_dpp v18, v18, v18 quad_perm:[2,3,0,1] row_mask:0xf bank_mask:0xf bound_ctrl:1
	v_add_f32_dpp v22, v22, v22 quad_perm:[2,3,0,1] row_mask:0xf bank_mask:0xf bound_ctrl:1
	ds_read_b128 v[44:47], v139 offset:5632
	v_add_f32_dpp v18, v18, v18 row_half_mirror row_mask:0xf bank_mask:0xf bound_ctrl:1
	v_add_f32_dpp v22, v22, v22 row_half_mirror row_mask:0xf bank_mask:0xf bound_ctrl:1
	ds_read_b128 v[40:43], v139 offset:5376
	v_add_f32_dpp v18, v18, v18 row_ror:8 row_mask:0xf bank_mask:0xf bound_ctrl:1
	v_add_f32_dpp v22, v22, v22 row_ror:8 row_mask:0xf bank_mask:0xf bound_ctrl:1
	ds_read_b128 v[48:51], v139 offset:5888
	v_pk_fma_f32 v[0:1], v[92:93], v[18:19], v[4:5] op_sel_hi:[1,0,1] neg_lo:[1,0,0] neg_hi:[1,0,0]
	v_pk_fma_f32 v[2:3], v[94:95], v[18:19], v[6:7] op_sel_hi:[1,0,1] neg_lo:[1,0,0] neg_hi:[1,0,0]
	v_cndmask_b32_e64 v23, v23, v22, s[38:39]
	ds_read_b128 v[56:59], v139 offset:6400
	s_waitcnt lgkmcnt(7)
	v_pk_mul_f32 v[8:9], v[118:119], v[126:127] op_sel_hi:[1,0]
	v_pk_mul_f32 v[10:11], v[120:121], v[126:127] op_sel_hi:[1,0]
	v_pk_mul_f32 v[16:17], v[0:1], v[110:111]
	v_pk_mul_f32 v[20:21], v[0:1], v[100:101]
	ds_read_b128 v[74:77], v139 offset:7488
	v_pk_fma_f32 v[16:17], v[2:3], v[112:113], v[16:17]
	v_pk_fma_f32 v[20:21], v[2:3], v[102:103], v[20:21]
	ds_read_b32 v82, v140 offset:6720
	v_add_f32_e32 v18, v16, v17
	v_add_f32_e32 v22, v20, v21
	v_pk_fma_f32 v[4:5], v[0:1], v[106:107], v[8:9]
	v_add_f32_dpp v18, v18, v18 quad_perm:[1,0,3,2] row_mask:0xf bank_mask:0xf bound_ctrl:1
	v_add_f32_dpp v22, v22, v22 quad_perm:[1,0,3,2] row_mask:0xf bank_mask:0xf bound_ctrl:1
	v_pk_fma_f32 v[6:7], v[2:3], v[108:109], v[10:11]
	v_add_f32_dpp v18, v18, v18 quad_perm:[2,3,0,1] row_mask:0xf bank_mask:0xf bound_ctrl:1
	v_add_f32_dpp v22, v22, v22 quad_perm:[2,3,0,1] row_mask:0xf bank_mask:0xf bound_ctrl:1
	ds_read_b128 v[66:69], v139 offset:6976
	v_add_f32_dpp v18, v18, v18 row_half_mirror row_mask:0xf bank_mask:0xf bound_ctrl:1
	v_add_f32_dpp v22, v22, v22 row_half_mirror row_mask:0xf bank_mask:0xf bound_ctrl:1
	ds_read_b128 v[62:65], v139 offset:6720
	v_add_f32_dpp v18, v18, v18 row_ror:8 row_mask:0xf bank_mask:0xf bound_ctrl:1
	v_add_f32_dpp v22, v22, v22 row_ror:8 row_mask:0xf bank_mask:0xf bound_ctrl:1
	ds_read_b128 v[70:73], v139 offset:7232
	v_pk_fma_f32 v[0:1], v[114:115], v[18:19], v[4:5] op_sel_hi:[1,0,1] neg_lo:[1,0,0] neg_hi:[1,0,0]
	v_pk_fma_f32 v[2:3], v[116:117], v[18:19], v[6:7] op_sel_hi:[1,0,1] neg_lo:[1,0,0] neg_hi:[1,0,0]
	v_cndmask_b32_e64 v23, v23, v22, s[40:41]
	ds_read_b128 v[78:81], v139 offset:7744
	s_waitcnt lgkmcnt(7)
	v_pk_mul_f32 v[8:9], v[52:53], v[60:61] op_sel_hi:[1,0]
	v_pk_mul_f32 v[10:11], v[54:55], v[60:61] op_sel_hi:[1,0]
	v_pk_mul_f32 v[16:17], v[0:1], v[44:45]
	v_pk_mul_f32 v[20:21], v[0:1], v[122:123]
	ds_read_b128 v[96:99], v139 offset:8832
	v_pk_fma_f32 v[16:17], v[2:3], v[46:47], v[16:17]
	v_pk_fma_f32 v[20:21], v[2:3], v[124:125], v[20:21]
	ds_read_b32 v104, v140 offset:8064
	v_add_f32_e32 v18, v16, v17
	v_add_f32_e32 v22, v20, v21
	v_pk_fma_f32 v[4:5], v[0:1], v[40:41], v[8:9]
	v_add_f32_dpp v18, v18, v18 quad_perm:[1,0,3,2] row_mask:0xf bank_mask:0xf bound_ctrl:1
	v_add_f32_dpp v22, v22, v22 quad_perm:[1,0,3,2] row_mask:0xf bank_mask:0xf bound_ctrl:1
	v_pk_fma_f32 v[6:7], v[2:3], v[42:43], v[10:11]
	v_add_f32_dpp v18, v18, v18 quad_perm:[2,3,0,1] row_mask:0xf bank_mask:0xf bound_ctrl:1
	v_add_f32_dpp v22, v22, v22 quad_perm:[2,3,0,1] row_mask:0xf bank_mask:0xf bound_ctrl:1
	ds_read_b128 v[88:91], v139 offset:8320
	v_add_f32_dpp v18, v18, v18 row_half_mirror row_mask:0xf bank_mask:0xf bound_ctrl:1
	v_add_f32_dpp v22, v22, v22 row_half_mirror row_mask:0xf bank_mask:0xf bound_ctrl:1
	ds_read_b128 v[84:87], v139 offset:8064
	v_add_f32_dpp v18, v18, v18 row_ror:8 row_mask:0xf bank_mask:0xf bound_ctrl:1
	v_add_f32_dpp v22, v22, v22 row_ror:8 row_mask:0xf bank_mask:0xf bound_ctrl:1
	ds_read_b128 v[92:95], v139 offset:8576
	v_pk_fma_f32 v[0:1], v[48:49], v[18:19], v[4:5] op_sel_hi:[1,0,1] neg_lo:[1,0,0] neg_hi:[1,0,0]
	v_pk_fma_f32 v[2:3], v[50:51], v[18:19], v[6:7] op_sel_hi:[1,0,1] neg_lo:[1,0,0] neg_hi:[1,0,0]
	v_cndmask_b32_e64 v23, v23, v22, s[42:43]
	ds_read_b128 v[100:103], v139 offset:9088
	s_waitcnt lgkmcnt(7)
	v_pk_mul_f32 v[8:9], v[74:75], v[82:83] op_sel_hi:[1,0]
	v_pk_mul_f32 v[10:11], v[76:77], v[82:83] op_sel_hi:[1,0]
	v_pk_mul_f32 v[16:17], v[0:1], v[66:67]
	v_pk_mul_f32 v[20:21], v[0:1], v[56:57]
	ds_read_b128 v[118:121], v139 offset:10176
	v_pk_fma_f32 v[16:17], v[2:3], v[68:69], v[16:17]
	v_pk_fma_f32 v[20:21], v[2:3], v[58:59], v[20:21]
	ds_read_b32 v126, v140 offset:9408
	v_add_f32_e32 v18, v16, v17
	v_add_f32_e32 v22, v20, v21
	v_pk_fma_f32 v[4:5], v[0:1], v[62:63], v[8:9]
	v_add_f32_dpp v18, v18, v18 quad_perm:[1,0,3,2] row_mask:0xf bank_mask:0xf bound_ctrl:1
	v_add_f32_dpp v22, v22, v22 quad_perm:[1,0,3,2] row_mask:0xf bank_mask:0xf bound_ctrl:1
	v_pk_fma_f32 v[6:7], v[2:3], v[64:65], v[10:11]
	v_add_f32_dpp v18, v18, v18 quad_perm:[2,3,0,1] row_mask:0xf bank_mask:0xf bound_ctrl:1
	v_add_f32_dpp v22, v22, v22 quad_perm:[2,3,0,1] row_mask:0xf bank_mask:0xf bound_ctrl:1
	ds_read_b128 v[110:113], v139 offset:9664
	v_add_f32_dpp v18, v18, v18 row_half_mirror row_mask:0xf bank_mask:0xf bound_ctrl:1
	v_add_f32_dpp v22, v22, v22 row_half_mirror row_mask:0xf bank_mask:0xf bound_ctrl:1
	ds_read_b128 v[106:109], v139 offset:9408
	v_add_f32_dpp v18, v18, v18 row_ror:8 row_mask:0xf bank_mask:0xf bound_ctrl:1
	v_add_f32_dpp v22, v22, v22 row_ror:8 row_mask:0xf bank_mask:0xf bound_ctrl:1
	ds_read_b128 v[114:117], v139 offset:9920
	v_pk_fma_f32 v[0:1], v[70:71], v[18:19], v[4:5] op_sel_hi:[1,0,1] neg_lo:[1,0,0] neg_hi:[1,0,0]
	v_pk_fma_f32 v[2:3], v[72:73], v[18:19], v[6:7] op_sel_hi:[1,0,1] neg_lo:[1,0,0] neg_hi:[1,0,0]
	v_cndmask_b32_e64 v23, v23, v22, s[44:45]
	ds_read_b128 v[122:125], v139 offset:10432
	s_waitcnt lgkmcnt(7)
	v_pk_mul_f32 v[8:9], v[96:97], v[104:105] op_sel_hi:[1,0]
	v_pk_mul_f32 v[10:11], v[98:99], v[104:105] op_sel_hi:[1,0]
	v_pk_mul_f32 v[16:17], v[0:1], v[88:89]
	v_pk_mul_f32 v[20:21], v[0:1], v[78:79]
	ds_read_b128 v[52:55], v139 offset:11520
	v_pk_fma_f32 v[16:17], v[2:3], v[90:91], v[16:17]
	v_pk_fma_f32 v[20:21], v[2:3], v[80:81], v[20:21]
	ds_read_b32 v60, v140 offset:10752
	v_add_f32_e32 v18, v16, v17
	v_add_f32_e32 v22, v20, v21
	v_pk_fma_f32 v[4:5], v[0:1], v[84:85], v[8:9]
	v_add_f32_dpp v18, v18, v18 quad_perm:[1,0,3,2] row_mask:0xf bank_mask:0xf bound_ctrl:1
	v_add_f32_dpp v22, v22, v22 quad_perm:[1,0,3,2] row_mask:0xf bank_mask:0xf bound_ctrl:1
	v_pk_fma_f32 v[6:7], v[2:3], v[86:87], v[10:11]
	v_add_f32_dpp v18, v18, v18 quad_perm:[2,3,0,1] row_mask:0xf bank_mask:0xf bound_ctrl:1
	v_add_f32_dpp v22, v22, v22 quad_perm:[2,3,0,1] row_mask:0xf bank_mask:0xf bound_ctrl:1
	ds_read_b128 v[44:47], v139 offset:11008
	v_add_f32_dpp v18, v18, v18 row_half_mirror row_mask:0xf bank_mask:0xf bound_ctrl:1
	v_add_f32_dpp v22, v22, v22 row_half_mirror row_mask:0xf bank_mask:0xf bound_ctrl:1
	ds_read_b128 v[40:43], v139 offset:10752
	v_add_f32_dpp v18, v18, v18 row_ror:8 row_mask:0xf bank_mask:0xf bound_ctrl:1
	v_add_f32_dpp v22, v22, v22 row_ror:8 row_mask:0xf bank_mask:0xf bound_ctrl:1
	ds_read_b128 v[48:51], v139 offset:11264
	v_pk_fma_f32 v[0:1], v[92:93], v[18:19], v[4:5] op_sel_hi:[1,0,1] neg_lo:[1,0,0] neg_hi:[1,0,0]
	v_pk_fma_f32 v[2:3], v[94:95], v[18:19], v[6:7] op_sel_hi:[1,0,1] neg_lo:[1,0,0] neg_hi:[1,0,0]
	v_cndmask_b32_e64 v23, v23, v22, s[46:47]
	ds_read_b128 v[56:59], v139 offset:11776
	s_waitcnt lgkmcnt(7)
	v_pk_mul_f32 v[8:9], v[118:119], v[126:127] op_sel_hi:[1,0]
	v_pk_mul_f32 v[10:11], v[120:121], v[126:127] op_sel_hi:[1,0]
	v_pk_mul_f32 v[16:17], v[0:1], v[110:111]
	v_pk_mul_f32 v[20:21], v[0:1], v[100:101]
	ds_read_b128 v[74:77], v139 offset:12864
	v_pk_fma_f32 v[16:17], v[2:3], v[112:113], v[16:17]
	v_pk_fma_f32 v[20:21], v[2:3], v[102:103], v[20:21]
	ds_read_b32 v82, v140 offset:12096
	v_add_f32_e32 v18, v16, v17
	v_add_f32_e32 v22, v20, v21
	v_pk_fma_f32 v[4:5], v[0:1], v[106:107], v[8:9]
	v_add_f32_dpp v18, v18, v18 quad_perm:[1,0,3,2] row_mask:0xf bank_mask:0xf bound_ctrl:1
	v_add_f32_dpp v22, v22, v22 quad_perm:[1,0,3,2] row_mask:0xf bank_mask:0xf bound_ctrl:1
	v_pk_fma_f32 v[6:7], v[2:3], v[108:109], v[10:11]
	v_add_f32_dpp v18, v18, v18 quad_perm:[2,3,0,1] row_mask:0xf bank_mask:0xf bound_ctrl:1
	v_add_f32_dpp v22, v22, v22 quad_perm:[2,3,0,1] row_mask:0xf bank_mask:0xf bound_ctrl:1
	ds_read_b128 v[66:69], v139 offset:12352
	v_add_f32_dpp v18, v18, v18 row_half_mirror row_mask:0xf bank_mask:0xf bound_ctrl:1
	v_add_f32_dpp v22, v22, v22 row_half_mirror row_mask:0xf bank_mask:0xf bound_ctrl:1
	ds_read_b128 v[62:65], v139 offset:12096
	v_add_f32_dpp v18, v18, v18 row_ror:8 row_mask:0xf bank_mask:0xf bound_ctrl:1
	v_add_f32_dpp v22, v22, v22 row_ror:8 row_mask:0xf bank_mask:0xf bound_ctrl:1
	ds_read_b128 v[70:73], v139 offset:12608
	v_pk_fma_f32 v[0:1], v[114:115], v[18:19], v[4:5] op_sel_hi:[1,0,1] neg_lo:[1,0,0] neg_hi:[1,0,0]
	v_pk_fma_f32 v[2:3], v[116:117], v[18:19], v[6:7] op_sel_hi:[1,0,1] neg_lo:[1,0,0] neg_hi:[1,0,0]
	v_cndmask_b32_e64 v23, v23, v22, s[48:49]
	ds_read_b128 v[78:81], v139 offset:13120
	s_waitcnt lgkmcnt(7)
	v_pk_mul_f32 v[8:9], v[52:53], v[60:61] op_sel_hi:[1,0]
	v_pk_mul_f32 v[10:11], v[54:55], v[60:61] op_sel_hi:[1,0]
	v_pk_mul_f32 v[16:17], v[0:1], v[44:45]
	v_pk_mul_f32 v[20:21], v[0:1], v[122:123]
	ds_read_b128 v[96:99], v139 offset:14208
	v_pk_fma_f32 v[16:17], v[2:3], v[46:47], v[16:17]
	v_pk_fma_f32 v[20:21], v[2:3], v[124:125], v[20:21]
	ds_read_b32 v104, v140 offset:13440
	v_add_f32_e32 v18, v16, v17
	v_add_f32_e32 v22, v20, v21
	v_pk_fma_f32 v[4:5], v[0:1], v[40:41], v[8:9]
	v_add_f32_dpp v18, v18, v18 quad_perm:[1,0,3,2] row_mask:0xf bank_mask:0xf bound_ctrl:1
	v_add_f32_dpp v22, v22, v22 quad_perm:[1,0,3,2] row_mask:0xf bank_mask:0xf bound_ctrl:1
	v_pk_fma_f32 v[6:7], v[2:3], v[42:43], v[10:11]
	v_add_f32_dpp v18, v18, v18 quad_perm:[2,3,0,1] row_mask:0xf bank_mask:0xf bound_ctrl:1
	v_add_f32_dpp v22, v22, v22 quad_perm:[2,3,0,1] row_mask:0xf bank_mask:0xf bound_ctrl:1
	ds_read_b128 v[88:91], v139 offset:13696
	v_add_f32_dpp v18, v18, v18 row_half_mirror row_mask:0xf bank_mask:0xf bound_ctrl:1
	v_add_f32_dpp v22, v22, v22 row_half_mirror row_mask:0xf bank_mask:0xf bound_ctrl:1
	ds_read_b128 v[84:87], v139 offset:13440
	v_add_f32_dpp v18, v18, v18 row_ror:8 row_mask:0xf bank_mask:0xf bound_ctrl:1
	v_add_f32_dpp v22, v22, v22 row_ror:8 row_mask:0xf bank_mask:0xf bound_ctrl:1
	ds_read_b128 v[92:95], v139 offset:13952
	v_pk_fma_f32 v[0:1], v[48:49], v[18:19], v[4:5] op_sel_hi:[1,0,1] neg_lo:[1,0,0] neg_hi:[1,0,0]
	v_pk_fma_f32 v[2:3], v[50:51], v[18:19], v[6:7] op_sel_hi:[1,0,1] neg_lo:[1,0,0] neg_hi:[1,0,0]
	v_cndmask_b32_e64 v23, v23, v22, s[50:51]
	ds_read_b128 v[100:103], v139 offset:14464
	s_waitcnt lgkmcnt(7)
	v_pk_mul_f32 v[8:9], v[74:75], v[82:83] op_sel_hi:[1,0]
	v_pk_mul_f32 v[10:11], v[76:77], v[82:83] op_sel_hi:[1,0]
	v_pk_mul_f32 v[16:17], v[0:1], v[66:67]
	v_pk_mul_f32 v[20:21], v[0:1], v[56:57]
	ds_read_b128 v[118:121], v139 offset:15552
	v_pk_fma_f32 v[16:17], v[2:3], v[68:69], v[16:17]
	v_pk_fma_f32 v[20:21], v[2:3], v[58:59], v[20:21]
	ds_read_b32 v126, v140 offset:14784
	v_add_f32_e32 v18, v16, v17
	v_add_f32_e32 v22, v20, v21
	v_pk_fma_f32 v[4:5], v[0:1], v[62:63], v[8:9]
	v_add_f32_dpp v18, v18, v18 quad_perm:[1,0,3,2] row_mask:0xf bank_mask:0xf bound_ctrl:1
	v_add_f32_dpp v22, v22, v22 quad_perm:[1,0,3,2] row_mask:0xf bank_mask:0xf bound_ctrl:1
	v_pk_fma_f32 v[6:7], v[2:3], v[64:65], v[10:11]
	v_add_f32_dpp v18, v18, v18 quad_perm:[2,3,0,1] row_mask:0xf bank_mask:0xf bound_ctrl:1
	v_add_f32_dpp v22, v22, v22 quad_perm:[2,3,0,1] row_mask:0xf bank_mask:0xf bound_ctrl:1
	ds_read_b128 v[110:113], v139 offset:15040
	v_add_f32_dpp v18, v18, v18 row_half_mirror row_mask:0xf bank_mask:0xf bound_ctrl:1
	v_add_f32_dpp v22, v22, v22 row_half_mirror row_mask:0xf bank_mask:0xf bound_ctrl:1
	ds_read_b128 v[106:109], v139 offset:14784
	v_add_f32_dpp v18, v18, v18 row_ror:8 row_mask:0xf bank_mask:0xf bound_ctrl:1
	v_add_f32_dpp v22, v22, v22 row_ror:8 row_mask:0xf bank_mask:0xf bound_ctrl:1
	ds_read_b128 v[114:117], v139 offset:15296
	v_pk_fma_f32 v[0:1], v[70:71], v[18:19], v[4:5] op_sel_hi:[1,0,1] neg_lo:[1,0,0] neg_hi:[1,0,0]
	v_pk_fma_f32 v[2:3], v[72:73], v[18:19], v[6:7] op_sel_hi:[1,0,1] neg_lo:[1,0,0] neg_hi:[1,0,0]
	v_cndmask_b32_e64 v23, v23, v22, s[52:53]
	ds_read_b128 v[122:125], v139 offset:15808
	s_waitcnt lgkmcnt(7)
	v_pk_mul_f32 v[8:9], v[96:97], v[104:105] op_sel_hi:[1,0]
	v_pk_mul_f32 v[10:11], v[98:99], v[104:105] op_sel_hi:[1,0]
	v_pk_mul_f32 v[16:17], v[0:1], v[88:89]
	v_pk_mul_f32 v[20:21], v[0:1], v[78:79]
	ds_read_b128 v[52:55], v139 offset:16896
	v_pk_fma_f32 v[16:17], v[2:3], v[90:91], v[16:17]
	v_pk_fma_f32 v[20:21], v[2:3], v[80:81], v[20:21]
	ds_read_b32 v60, v140 offset:16128
	v_add_f32_e32 v18, v16, v17
	v_add_f32_e32 v22, v20, v21
	v_pk_fma_f32 v[4:5], v[0:1], v[84:85], v[8:9]
	v_add_f32_dpp v18, v18, v18 quad_perm:[1,0,3,2] row_mask:0xf bank_mask:0xf bound_ctrl:1
	v_add_f32_dpp v22, v22, v22 quad_perm:[1,0,3,2] row_mask:0xf bank_mask:0xf bound_ctrl:1
	v_pk_fma_f32 v[6:7], v[2:3], v[86:87], v[10:11]
	v_add_f32_dpp v18, v18, v18 quad_perm:[2,3,0,1] row_mask:0xf bank_mask:0xf bound_ctrl:1
	v_add_f32_dpp v22, v22, v22 quad_perm:[2,3,0,1] row_mask:0xf bank_mask:0xf bound_ctrl:1
	ds_read_b128 v[44:47], v139 offset:16384
	v_add_f32_dpp v18, v18, v18 row_half_mirror row_mask:0xf bank_mask:0xf bound_ctrl:1
	v_add_f32_dpp v22, v22, v22 row_half_mirror row_mask:0xf bank_mask:0xf bound_ctrl:1
	ds_read_b128 v[40:43], v139 offset:16128
	v_add_f32_dpp v18, v18, v18 row_ror:8 row_mask:0xf bank_mask:0xf bound_ctrl:1
	v_add_f32_dpp v22, v22, v22 row_ror:8 row_mask:0xf bank_mask:0xf bound_ctrl:1
	ds_read_b128 v[48:51], v139 offset:16640
	v_pk_fma_f32 v[0:1], v[92:93], v[18:19], v[4:5] op_sel_hi:[1,0,1] neg_lo:[1,0,0] neg_hi:[1,0,0]
	v_pk_fma_f32 v[2:3], v[94:95], v[18:19], v[6:7] op_sel_hi:[1,0,1] neg_lo:[1,0,0] neg_hi:[1,0,0]
	v_cndmask_b32_e64 v23, v23, v22, s[54:55]
	ds_read_b128 v[56:59], v139 offset:17152
	s_waitcnt lgkmcnt(7)
	v_pk_mul_f32 v[8:9], v[118:119], v[126:127] op_sel_hi:[1,0]
	v_pk_mul_f32 v[10:11], v[120:121], v[126:127] op_sel_hi:[1,0]
	s_waitcnt vmcnt(0)
	ds_write_b128 v143, v[146:149]
	ds_write_b128 v143, v[150:153] offset:256
	ds_write_b128 v143, v[154:157] offset:512
	ds_write_b128 v143, v[158:161] offset:768
	ds_write_b128 v143, v[162:165] offset:1024
	ds_write_b32 v35, v166
	v_pk_mul_f32 v[16:17], v[0:1], v[110:111]
	v_pk_mul_f32 v[20:21], v[0:1], v[100:101]
	ds_read_b128 v[74:77], v139 offset:18240
	v_pk_fma_f32 v[16:17], v[2:3], v[112:113], v[16:17]
	v_pk_fma_f32 v[20:21], v[2:3], v[102:103], v[20:21]
	ds_read_b32 v82, v140 offset:17472
	v_add_f32_e32 v18, v16, v17
	v_add_f32_e32 v22, v20, v21
	v_pk_fma_f32 v[4:5], v[0:1], v[106:107], v[8:9]
	v_add_f32_dpp v18, v18, v18 quad_perm:[1,0,3,2] row_mask:0xf bank_mask:0xf bound_ctrl:1
	v_add_f32_dpp v22, v22, v22 quad_perm:[1,0,3,2] row_mask:0xf bank_mask:0xf bound_ctrl:1
	v_pk_fma_f32 v[6:7], v[2:3], v[108:109], v[10:11]
	v_add_f32_dpp v18, v18, v18 quad_perm:[2,3,0,1] row_mask:0xf bank_mask:0xf bound_ctrl:1
	v_add_f32_dpp v22, v22, v22 quad_perm:[2,3,0,1] row_mask:0xf bank_mask:0xf bound_ctrl:1
	ds_read_b128 v[66:69], v139 offset:17728
	v_add_f32_dpp v18, v18, v18 row_half_mirror row_mask:0xf bank_mask:0xf bound_ctrl:1
	v_add_f32_dpp v22, v22, v22 row_half_mirror row_mask:0xf bank_mask:0xf bound_ctrl:1
	ds_read_b128 v[62:65], v139 offset:17472
	v_add_f32_dpp v18, v18, v18 row_ror:8 row_mask:0xf bank_mask:0xf bound_ctrl:1
	v_add_f32_dpp v22, v22, v22 row_ror:8 row_mask:0xf bank_mask:0xf bound_ctrl:1
	ds_read_b128 v[70:73], v139 offset:17984
	v_pk_fma_f32 v[0:1], v[114:115], v[18:19], v[4:5] op_sel_hi:[1,0,1] neg_lo:[1,0,0] neg_hi:[1,0,0]
	v_pk_fma_f32 v[2:3], v[116:117], v[18:19], v[6:7] op_sel_hi:[1,0,1] neg_lo:[1,0,0] neg_hi:[1,0,0]
	v_cndmask_b32_e64 v23, v23, v22, s[56:57]
	ds_read_b128 v[78:81], v139 offset:18496
	s_waitcnt lgkmcnt(7)
	v_pk_mul_f32 v[8:9], v[52:53], v[60:61] op_sel_hi:[1,0]
	v_pk_mul_f32 v[10:11], v[54:55], v[60:61] op_sel_hi:[1,0]
	v_pk_mul_f32 v[16:17], v[0:1], v[44:45]
	v_pk_mul_f32 v[20:21], v[0:1], v[122:123]
	ds_read_b128 v[96:99], v139 offset:19584
	v_pk_fma_f32 v[16:17], v[2:3], v[46:47], v[16:17]
	v_pk_fma_f32 v[20:21], v[2:3], v[124:125], v[20:21]
	ds_read_b32 v104, v140 offset:18816
	v_add_f32_e32 v18, v16, v17
	v_add_f32_e32 v22, v20, v21
	v_pk_fma_f32 v[4:5], v[0:1], v[40:41], v[8:9]
	v_add_f32_dpp v18, v18, v18 quad_perm:[1,0,3,2] row_mask:0xf bank_mask:0xf bound_ctrl:1
	v_add_f32_dpp v22, v22, v22 quad_perm:[1,0,3,2] row_mask:0xf bank_mask:0xf bound_ctrl:1
	v_pk_fma_f32 v[6:7], v[2:3], v[42:43], v[10:11]
	v_add_f32_dpp v18, v18, v18 quad_perm:[2,3,0,1] row_mask:0xf bank_mask:0xf bound_ctrl:1
	v_add_f32_dpp v22, v22, v22 quad_perm:[2,3,0,1] row_mask:0xf bank_mask:0xf bound_ctrl:1
	ds_read_b128 v[88:91], v139 offset:19072
	v_add_f32_dpp v18, v18, v18 row_half_mirror row_mask:0xf bank_mask:0xf bound_ctrl:1
	v_add_f32_dpp v22, v22, v22 row_half_mirror row_mask:0xf bank_mask:0xf bound_ctrl:1
	ds_read_b128 v[84:87], v139 offset:18816
	v_add_f32_dpp v18, v18, v18 row_ror:8 row_mask:0xf bank_mask:0xf bound_ctrl:1
	v_add_f32_dpp v22, v22, v22 row_ror:8 row_mask:0xf bank_mask:0xf bound_ctrl:1
	ds_read_b128 v[92:95], v139 offset:19328
	v_pk_fma_f32 v[0:1], v[48:49], v[18:19], v[4:5] op_sel_hi:[1,0,1] neg_lo:[1,0,0] neg_hi:[1,0,0]
	v_pk_fma_f32 v[2:3], v[50:51], v[18:19], v[6:7] op_sel_hi:[1,0,1] neg_lo:[1,0,0] neg_hi:[1,0,0]
	v_cndmask_b32_e64 v23, v23, v22, s[58:59]
	ds_read_b128 v[100:103], v139 offset:19840
	s_waitcnt lgkmcnt(7)
	s_barrier
	s_add_i32 s0, s4, 2
	s_cmp_lt_u32 s0, s5
	s_cbranch_scc0 .Lscan_nold
	s_mul_i32 s92, s0, s90
	v_add_u32_e32 v132, s92, v28
	v_add_u32_e32 v133, s92, v29
	v_add_u32_e32 v134, s92, v30
	v_add_u32_e32 v135, s92, v31
	v_add_u32_e32 v136, s92, v32
	v_add_u32_e32 v137, s92, v33
	global_load_dwordx4 v[146:149], v132, s[96:97]
	global_load_dwordx4 v[150:153], v133, s[96:97]
	global_load_dwordx4 v[154:157], v134, s[96:97]
	global_load_dwordx4 v[158:161], v135, s[96:97]
	global_load_dwordx4 v[162:165], v136, s[96:97]
	global_load_dword v166, v137, s[96:97]
.Lscan_nold:
	v_pk_mul_f32 v[8:9], v[74:75], v[82:83] op_sel_hi:[1,0]
	v_pk_mul_f32 v[10:11], v[76:77], v[82:83] op_sel_hi:[1,0]
	v_pk_mul_f32 v[16:17], v[0:1], v[66:67]
	v_pk_mul_f32 v[20:21], v[0:1], v[56:57]
	ds_read_b128 v[118:121], v139 offset:20928
	v_pk_fma_f32 v[16:17], v[2:3], v[68:69], v[16:17]
	v_pk_fma_f32 v[20:21], v[2:3], v[58:59], v[20:21]
	ds_read_b32 v126, v140 offset:20160
	v_add_f32_e32 v18, v16, v17
	v_add_f32_e32 v22, v20, v21
	v_pk_fma_f32 v[4:5], v[0:1], v[62:63], v[8:9]
	v_add_f32_dpp v18, v18, v18 quad_perm:[1,0,3,2] row_mask:0xf bank_mask:0xf bound_ctrl:1
	v_add_f32_dpp v22, v22, v22 quad_perm:[1,0,3,2] row_mask:0xf bank_mask:0xf bound_ctrl:1
	v_pk_fma_f32 v[6:7], v[2:3], v[64:65], v[10:11]
	v_add_f32_dpp v18, v18, v18 quad_perm:[2,3,0,1] row_mask:0xf bank_mask:0xf bound_ctrl:1
	v_add_f32_dpp v22, v22, v22 quad_perm:[2,3,0,1] row_mask:0xf bank_mask:0xf bound_ctrl:1
	ds_read_b128 v[110:113], v139 offset:20416
	v_add_f32_dpp v18, v18, v18 row_half_mirror row_mask:0xf bank_mask:0xf bound_ctrl:1
	v_add_f32_dpp v22, v22, v22 row_half_mirror row_mask:0xf bank_mask:0xf bound_ctrl:1
	ds_read_b128 v[106:109], v139 offset:20160
	v_add_f32_dpp v18, v18, v18 row_ror:8 row_mask:0xf bank_mask:0xf bound_ctrl:1
	v_add_f32_dpp v22, v22, v22 row_ror:8 row_mask:0xf bank_mask:0xf bound_ctrl:1
	ds_read_b128 v[114:117], v139 offset:20672
	v_pk_fma_f32 v[0:1], v[70:71], v[18:19], v[4:5] op_sel_hi:[1,0,1] neg_lo:[1,0,0] neg_hi:[1,0,0]
	v_pk_fma_f32 v[2:3], v[72:73], v[18:19], v[6:7] op_sel_hi:[1,0,1] neg_lo:[1,0,0] neg_hi:[1,0,0]
	v_cndmask_b32_e64 v23, v23, v22, s[60:61]
	ds_read_b128 v[122:125], v139 offset:21184
	s_waitcnt lgkmcnt(7)
	v_pk_mul_f32 v[8:9], v[96:97], v[104:105] op_sel_hi:[1,0]
	v_pk_mul_f32 v[10:11], v[98:99], v[104:105] op_sel_hi:[1,0]
	v_pk_mul_f32 v[16:17], v[0:1], v[88:89]
	v_pk_mul_f32 v[20:21], v[0:1], v[78:79]
	ds_read_b128 v[52:55], v141 offset:768
	v_pk_fma_f32 v[16:17], v[2:3], v[90:91], v[16:17]
	v_pk_fma_f32 v[20:21], v[2:3], v[80:81], v[20:21]
	ds_read_b32 v60, v142 offset:0
	v_add_f32_e32 v18, v16, v17
	v_add_f32_e32 v22, v20, v21
	v_pk_fma_f32 v[4:5], v[0:1], v[84:85], v[8:9]
	v_add_f32_dpp v18, v18, v18 quad_perm:[1,0,3,2] row_mask:0xf bank_mask:0xf bound_ctrl:1
	v_add_f32_dpp v22, v22, v22 quad_perm:[1,0,3,2] row_mask:0xf bank_mask:0xf bound_ctrl:1
	v_pk_fma_f32 v[6:7], v[2:3], v[86:87], v[10:11]
	v_add_f32_dpp v18, v18, v18 quad_perm:[2,3,0,1] row_mask:0xf bank_mask:0xf bound_ctrl:1
	v_add_f32_dpp v22, v22, v22 quad_perm:[2,3,0,1] row_mask:0xf bank_mask:0xf bound_ctrl:1
	ds_read_b128 v[44:47], v141 offset:256
	v_add_f32_dpp v18, v18, v18 row_half_mirror row_mask:0xf bank_mask:0xf bound_ctrl:1
	v_add_f32_dpp v22, v22, v22 row_half_mirror row_mask:0xf bank_mask:0xf bound_ctrl:1
	ds_read_b128 v[40:43], v141 offset:0
	v_add_f32_dpp v18, v18, v18 row_ror:8 row_mask:0xf bank_mask:0xf bound_ctrl:1
	v_add_f32_dpp v22, v22, v22 row_ror:8 row_mask:0xf bank_mask:0xf bound_ctrl:1
	ds_read_b128 v[48:51], v141 offset:512
	v_pk_fma_f32 v[0:1], v[92:93], v[18:19], v[4:5] op_sel_hi:[1,0,1] neg_lo:[1,0,0] neg_hi:[1,0,0]
	v_pk_fma_f32 v[2:3], v[94:95], v[18:19], v[6:7] op_sel_hi:[1,0,1] neg_lo:[1,0,0] neg_hi:[1,0,0]
	v_cndmask_b32_e64 v23, v23, v22, s[62:63]
	ds_read_b128 v[56:59], v141 offset:1024
	s_waitcnt lgkmcnt(7)
	v_pk_mul_f32 v[8:9], v[118:119], v[126:127] op_sel_hi:[1,0]
	v_pk_mul_f32 v[10:11], v[120:121], v[126:127] op_sel_hi:[1,0]
	v_pk_mul_f32 v[16:17], v[0:1], v[110:111]
	v_pk_mul_f32 v[20:21], v[0:1], v[100:101]
	ds_read_b128 v[74:77], v141 offset:2112
	v_pk_fma_f32 v[16:17], v[2:3], v[112:113], v[16:17]
	v_pk_fma_f32 v[20:21], v[2:3], v[102:103], v[20:21]
	ds_read_b32 v82, v142 offset:1344
	v_add_f32_e32 v18, v16, v17
	v_add_f32_e32 v22, v20, v21
	v_pk_fma_f32 v[4:5], v[0:1], v[106:107], v[8:9]
	v_add_f32_dpp v18, v18, v18 quad_perm:[1,0,3,2] row_mask:0xf bank_mask:0xf bound_ctrl:1
	v_add_f32_dpp v22, v22, v22 quad_perm:[1,0,3,2] row_mask:0xf bank_mask:0xf bound_ctrl:1
	v_pk_fma_f32 v[6:7], v[2:3], v[108:109], v[10:11]
	v_add_f32_dpp v18, v18, v18 quad_perm:[2,3,0,1] row_mask:0xf bank_mask:0xf bound_ctrl:1
	v_add_f32_dpp v22, v22, v22 quad_perm:[2,3,0,1] row_mask:0xf bank_mask:0xf bound_ctrl:1
	ds_read_b128 v[66:69], v141 offset:1600
	v_add_f32_dpp v18, v18, v18 row_half_mirror row_mask:0xf bank_mask:0xf bound_ctrl:1
	v_add_f32_dpp v22, v22, v22 row_half_mirror row_mask:0xf bank_mask:0xf bound_ctrl:1
	ds_read_b128 v[62:65], v141 offset:1344
	v_add_f32_dpp v18, v18, v18 row_ror:8 row_mask:0xf bank_mask:0xf bound_ctrl:1
	v_add_f32_dpp v22, v22, v22 row_ror:8 row_mask:0xf bank_mask:0xf bound_ctrl:1
	ds_read_b128 v[70:73], v141 offset:1856
	v_pk_fma_f32 v[0:1], v[114:115], v[18:19], v[4:5] op_sel_hi:[1,0,1] neg_lo:[1,0,0] neg_hi:[1,0,0]
	v_pk_fma_f32 v[2:3], v[116:117], v[18:19], v[6:7] op_sel_hi:[1,0,1] neg_lo:[1,0,0] neg_hi:[1,0,0]
	v_cndmask_b32_e64 v23, v23, v22, s[64:65]
	ds_read_b128 v[78:81], v141 offset:2368
	s_waitcnt lgkmcnt(7)
	v_pk_mul_f32 v[8:9], v[52:53], v[60:61] op_sel_hi:[1,0]
	v_pk_mul_f32 v[10:11], v[54:55], v[60:61] op_sel_hi:[1,0]
	s_add_i32 s4, s4, 1
	s_mov_b32 s0, s6
	s_mov_b32 s6, s7
	s_mov_b32 s7, s25
	s_mov_b32 s25, s0
	v_mov_b32_e32 v139, v141
	v_mov_b32_e32 v140, v142
	v_add_u32_e32 v141, s7, v24
	v_add_u32_e32 v142, s7, v25
	v_add_u32_e32 v143, s7, v26
	v_add_u32_e32 v35, s7, v27
	s_cmp_lt_u32 s4, s5
	s_cbranch_scc1 .Lscan_chunk
	v_mul_f32_e32 v20, v0, v122
	v_fmac_f32_e32 v20, v1, v123
	v_fmac_f32_e32 v20, v2, v124
	v_fmac_f32_e32 v20, v3, v125
	s_nop 1
	v_add_f32_dpp v20, v20, v20 quad_perm:[1,0,3,2] row_mask:0xf bank_mask:0xf bound_ctrl:1
	s_nop 1
	v_add_f32_dpp v20, v20, v20 quad_perm:[2,3,0,1] row_mask:0xf bank_mask:0xf bound_ctrl:1
	s_nop 1
	v_add_f32_dpp v20, v20, v20 row_half_mirror row_mask:0xf bank_mask:0xf bound_ctrl:1
	s_nop 1
	v_add_f32_dpp v20, v20, v20 row_ror:8 row_mask:0xf bank_mask:0xf bound_ctrl:1
	v_cndmask_b32_e64 v23, v23, v20, s[66:67]
	global_store_dword v138, v23, s[96:97]
	s_cmp_eq_u32 s28, 0
	s_cbranch_scc1 .Lscan_done
	v_readlane_b32 s0, v254, 57
	v_readlane_b32 s1, v254, 58
	s_nop 4
	global_store_dwordx4 v39, v[0:3], s[0:1]
.Lscan_done:
	s_waitcnt lgkmcnt(0)
	s_setprio 0
	s_branch .LBB0_100

.LBB0_271:
	v_and_b32_e32 v150, 63, v128
	v_lshrrev_b32_e32 v151, 6, v128
	v_lshrrev_b32_e32 v152, 3, v150
	v_readfirstlane_b32 s0, v151
	v_and_b32_e32 v153, 7, v150
	v_xor_b32_e32 v153, v153, v152
	v_lshlrev_b32_e32 v153, 4, v153
	v_lshl_add_u32 v153, v152, 11, v153
	s_lshl_b32 s1, s0, 16
	v_add_u32_e32 v132, s1, v153
	v_add_u32_e32 v133, 0x3c00, v132
	v_add_u32_e32 v134, 0x7800, v132
	v_add_u32_e32 v135, 0xb400, v132
	s_lshl_b32 s1, s0, 12
	s_add_u32 s5, s1, 0
	s_add_u32 s6, s1, 16384
	s_add_u32 s7, s1, 45056
	s_add_u32 s8, s1, 61440
	v_and_b32_e32 v152, 15, v150
	v_lshrrev_b32_e32 v153, 4, v150
	v_and_b32_e32 v154, 7, v152
	v_xor_b32_e32 v154, v154, v153
	v_lshlrev_b32_e32 v154, 4, v154
	v_lshl_add_u32 v154, v152, 7, v154
	s_lshr_b32 s1, s0, 1
	s_lshl_b32 s1, s1, 13
	v_add_u32_e32 v136, s1, v154
	v_xor_b32_e32 v137, 64, v136
	v_add_u32_e32 v138, 0xb000, v136
	v_add_u32_e32 v139, 0xb000, v137
	s_and_b32 s1, s0, 1
	s_lshl_b32 s1, s1, 13
	s_add_u32 s1, s1, 16384
	v_add_u32_e32 v140, s1, v154
	v_xor_b32_e32 v141, 64, v140
	v_add_u32_e32 v142, 0xb000, v140
	v_add_u32_e32 v143, 0xb000, v141
	s_and_b32 s1, s0, 1
	s_lshl_b32 s1, s1, 6
	v_add_u32_e32 v152, s1, v152
	v_mov_b32_e32 v154, 0x4a00
	v_mul_lo_u32 v152, v152, v154
	v_lshlrev_b32_e32 v153, 3, v153
	s_lshr_b32 s1, s0, 1
	s_lshl_b32 s1, s1, 7
	v_add3_u32 v146, v152, v153, s1
	v_add_u32_e32 v147, 0x4a000, v146
	v_add_u32_e32 v148, 0x94000, v146
	v_add_u32_e32 v149, 0xde000, v146
	v_readlane_b32 s25, v252, 0
	s_and_b32 s0, s25, 63
	s_lshr_b32 s1, s25, 6
	s_mul_i32 s4, s70, 0x1280000
	s_lshl_b32 s39, s1, 18
	s_add_u32 s4, s4, s39
	s_add_u32 s26, s96, s4
	s_addc_u32 s27, s97, 0
	s_lshl_b32 s4, s0, 18
	s_add_u32 s4, s4, 0x82a6100
	s_add_u32 s28, s96, s4
	s_addc_u32 s29, s97, 0
	s_mov_b32 m0, s5
	s_nop 0
	global_load_lds_dwordx4 v132, s[26:27] offset:0
	global_load_lds_dwordx4 v133, s[26:27] offset:1024
	global_load_lds_dwordx4 v134, s[26:27] offset:2048
	global_load_lds_dwordx4 v135, s[26:27] offset:3072
	s_mov_b32 m0, s6
	s_nop 0
	global_load_lds_dwordx4 v132, s[28:29] offset:0
	global_load_lds_dwordx4 v133, s[28:29] offset:1024
	global_load_lds_dwordx4 v134, s[28:29] offset:2048
	global_load_lds_dwordx4 v135, s[28:29] offset:3072
	s_waitcnt vmcnt(0)
.Lgin_tile:
	s_waitcnt vmcnt(16)
	s_barrier
	s_add_u32 s26, s26, 0x80
	s_addc_u32 s27, s27, 0
	s_add_u32 s28, s28, 0x80
	s_addc_u32 s29, s29, 0
	s_mov_b32 m0, s7
	s_nop 0
	global_load_lds_dwordx4 v132, s[26:27] offset:0
	global_load_lds_dwordx4 v133, s[26:27] offset:1024
	global_load_lds_dwordx4 v134, s[26:27] offset:2048
	global_load_lds_dwordx4 v135, s[26:27] offset:3072
	s_mov_b32 m0, s8
	s_nop 0
	global_load_lds_dwordx4 v132, s[28:29] offset:0
	global_load_lds_dwordx4 v133, s[28:29] offset:1024
	global_load_lds_dwordx4 v134, s[28:29] offset:2048
	global_load_lds_dwordx4 v135, s[28:29] offset:3072
	ds_read_b128 v[64:67], v136 offset:0
	ds_read_b128 v[96:99], v140 offset:0
	ds_read_b128 v[100:103], v140 offset:2048
	ds_read_b128 v[104:107], v140 offset:4096
	ds_read_b128 v[108:111], v140 offset:6144
	ds_read_b128 v[68:71], v136 offset:2048
	ds_read_b128 v[72:75], v136 offset:4096
	ds_read_b128 v[76:79], v136 offset:6144
	s_waitcnt lgkmcnt(3)
	v_mfma_f32_16x16x32_bf16 v[0:3], v[64:67], v[96:99], 0
	v_mfma_f32_16x16x32_bf16 v[4:7], v[64:67], v[100:103], 0
	ds_read_b128 v[80:83], v137 offset:0
	v_mfma_f32_16x16x32_bf16 v[8:11], v[64:67], v[104:107], 0
	v_mfma_f32_16x16x32_bf16 v[12:15], v[64:67], v[108:111], 0
	ds_read_b128 v[112:115], v141 offset:0
	s_waitcnt lgkmcnt(4)
	v_mfma_f32_16x16x32_bf16 v[16:19], v[68:71], v[96:99], 0
	v_mfma_f32_16x16x32_bf16 v[20:23], v[68:71], v[100:103], 0
	ds_read_b128 v[116:119], v141 offset:2048
	v_mfma_f32_16x16x32_bf16 v[24:27], v[68:71], v[104:107], 0
	v_mfma_f32_16x16x32_bf16 v[28:31], v[68:71], v[108:111], 0
	ds_read_b128 v[120:123], v141 offset:4096
	s_waitcnt lgkmcnt(5)
	v_mfma_f32_16x16x32_bf16 v[32:35], v[72:75], v[96:99], 0
	v_mfma_f32_16x16x32_bf16 v[36:39], v[72:75], v[100:103], 0
	ds_read_b128 v[124:127], v141 offset:6144
	v_mfma_f32_16x16x32_bf16 v[40:43], v[72:75], v[104:107], 0
	v_mfma_f32_16x16x32_bf16 v[44:47], v[72:75], v[108:111], 0
	ds_read_b128 v[84:87], v137 offset:2048
	s_waitcnt lgkmcnt(6)
	v_mfma_f32_16x16x32_bf16 v[48:51], v[76:79], v[96:99], 0
	v_mfma_f32_16x16x32_bf16 v[52:55], v[76:79], v[100:103], 0
	ds_read_b128 v[88:91], v137 offset:4096
	v_mfma_f32_16x16x32_bf16 v[56:59], v[76:79], v[104:107], 0
	v_mfma_f32_16x16x32_bf16 v[60:63], v[76:79], v[108:111], 0
	ds_read_b128 v[92:95], v137 offset:6144
	s_waitcnt lgkmcnt(3)
	v_mfma_f32_16x16x32_bf16 v[0:3], v[80:83], v[112:115], v[0:3]
	v_mfma_f32_16x16x32_bf16 v[4:7], v[80:83], v[116:119], v[4:7]
	v_mfma_f32_16x16x32_bf16 v[8:11], v[80:83], v[120:123], v[8:11]
	v_mfma_f32_16x16x32_bf16 v[12:15], v[80:83], v[124:127], v[12:15]
	s_waitcnt lgkmcnt(2)
	v_mfma_f32_16x16x32_bf16 v[16:19], v[84:87], v[112:115], v[16:19]
	v_mfma_f32_16x16x32_bf16 v[20:23], v[84:87], v[116:119], v[20:23]
	v_mfma_f32_16x16x32_bf16 v[24:27], v[84:87], v[120:123], v[24:27]
	v_mfma_f32_16x16x32_bf16 v[28:31], v[84:87], v[124:127], v[28:31]
	s_waitcnt lgkmcnt(1)
	v_mfma_f32_16x16x32_bf16 v[32:35], v[88:91], v[112:115], v[32:35]
	v_mfma_f32_16x16x32_bf16 v[36:39], v[88:91], v[116:119], v[36:39]
	v_mfma_f32_16x16x32_bf16 v[40:43], v[88:91], v[120:123], v[40:43]
	v_mfma_f32_16x16x32_bf16 v[44:47], v[88:91], v[124:127], v[44:47]
	s_waitcnt lgkmcnt(0)
	v_mfma_f32_16x16x32_bf16 v[48:51], v[92:95], v[112:115], v[48:51]
	v_mfma_f32_16x16x32_bf16 v[52:55], v[92:95], v[116:119], v[52:55]
	v_mfma_f32_16x16x32_bf16 v[56:59], v[92:95], v[120:123], v[56:59]
	v_mfma_f32_16x16x32_bf16 v[60:63], v[92:95], v[124:127], v[60:63]
	s_waitcnt vmcnt(0)
	s_barrier
	s_add_u32 s26, s26, 0x80
	s_addc_u32 s27, s27, 0
	s_add_u32 s28, s28, 0x80
	s_addc_u32 s29, s29, 0
	s_mov_b32 m0, s5
	s_nop 0
	global_load_lds_dwordx4 v132, s[26:27] offset:0
	global_load_lds_dwordx4 v133, s[26:27] offset:1024
	global_load_lds_dwordx4 v134, s[26:27] offset:2048
	global_load_lds_dwordx4 v135, s[26:27] offset:3072
	s_mov_b32 m0, s6
	s_nop 0
	global_load_lds_dwordx4 v132, s[28:29] offset:0
	global_load_lds_dwordx4 v133, s[28:29] offset:1024
	global_load_lds_dwordx4 v134, s[28:29] offset:2048
	global_load_lds_dwordx4 v135, s[28:29] offset:3072
	ds_read_b128 v[64:67], v138 offset:0
	ds_read_b128 v[96:99], v142 offset:0
	ds_read_b128 v[100:103], v142 offset:2048
	ds_read_b128 v[104:107], v142 offset:4096
	ds_read_b128 v[108:111], v142 offset:6144
	ds_read_b128 v[68:71], v138 offset:2048
	ds_read_b128 v[72:75], v138 offset:4096
	ds_read_b128 v[76:79], v138 offset:6144
	s_waitcnt lgkmcnt(3)
	v_mfma_f32_16x16x32_bf16 v[0:3], v[64:67], v[96:99], v[0:3]
	v_mfma_f32_16x16x32_bf16 v[4:7], v[64:67], v[100:103], v[4:7]
	ds_read_b128 v[80:83], v139 offset:0
	v_mfma_f32_16x16x32_bf16 v[8:11], v[64:67], v[104:107], v[8:11]
	v_mfma_f32_16x16x32_bf16 v[12:15], v[64:67], v[108:111], v[12:15]
	ds_read_b128 v[112:115], v143 offset:0
	s_waitcnt lgkmcnt(4)
	v_mfma_f32_16x16x32_bf16 v[16:19], v[68:71], v[96:99], v[16:19]
	v_mfma_f32_16x16x32_bf16 v[20:23], v[68:71], v[100:103], v[20:23]
	ds_read_b128 v[116:119], v143 offset:2048
	v_mfma_f32_16x16x32_bf16 v[24:27], v[68:71], v[104:107], v[24:27]
	v_mfma_f32_16x16x32_bf16 v[28:31], v[68:71], v[108:111], v[28:31]
	ds_read_b128 v[120:123], v143 offset:4096
	s_waitcnt lgkmcnt(5)
	v_mfma_f32_16x16x32_bf16 v[32:35], v[72:75], v[96:99], v[32:35]
	v_mfma_f32_16x16x32_bf16 v[36:39], v[72:75], v[100:103], v[36:39]
	ds_read_b128 v[124:127], v143 offset:6144
	v_mfma_f32_16x16x32_bf16 v[40:43], v[72:75], v[104:107], v[40:43]
	v_mfma_f32_16x16x32_bf16 v[44:47], v[72:75], v[108:111], v[44:47]
	ds_read_b128 v[84:87], v139 offset:2048
	s_waitcnt lgkmcnt(6)
	v_mfma_f32_16x16x32_bf16 v[48:51], v[76:79], v[96:99], v[48:51]
	v_mfma_f32_16x16x32_bf16 v[52:55], v[76:79], v[100:103], v[52:55]
	ds_read_b128 v[88:91], v139 offset:4096
	v_mfma_f32_16x16x32_bf16 v[56:59], v[76:79], v[104:107], v[56:59]
	v_mfma_f32_16x16x32_bf16 v[60:63], v[76:79], v[108:111], v[60:63]
	ds_read_b128 v[92:95], v139 offset:6144
	s_waitcnt lgkmcnt(3)
	v_mfma_f32_16x16x32_bf16 v[0:3], v[80:83], v[112:115], v[0:3]
	v_mfma_f32_16x16x32_bf16 v[4:7], v[80:83], v[116:119], v[4:7]
	v_mfma_f32_16x16x32_bf16 v[8:11], v[80:83], v[120:123], v[8:11]
	v_mfma_f32_16x16x32_bf16 v[12:15], v[80:83], v[124:127], v[12:15]
	s_waitcnt lgkmcnt(2)
	v_mfma_f32_16x16x32_bf16 v[16:19], v[84:87], v[112:115], v[16:19]
	v_mfma_f32_16x16x32_bf16 v[20:23], v[84:87], v[116:119], v[20:23]
	v_mfma_f32_16x16x32_bf16 v[24:27], v[84:87], v[120:123], v[24:27]
	v_mfma_f32_16x16x32_bf16 v[28:31], v[84:87], v[124:127], v[28:31]
	s_waitcnt lgkmcnt(1)
	v_mfma_f32_16x16x32_bf16 v[32:35], v[88:91], v[112:115], v[32:35]
	v_mfma_f32_16x16x32_bf16 v[36:39], v[88:91], v[116:119], v[36:39]
	v_mfma_f32_16x16x32_bf16 v[40:43], v[88:91], v[120:123], v[40:43]
	v_mfma_f32_16x16x32_bf16 v[44:47], v[88:91], v[124:127], v[44:47]
	s_waitcnt lgkmcnt(0)
	v_mfma_f32_16x16x32_bf16 v[48:51], v[92:95], v[112:115], v[48:51]
	v_mfma_f32_16x16x32_bf16 v[52:55], v[92:95], v[116:119], v[52:55]
	v_mfma_f32_16x16x32_bf16 v[56:59], v[92:95], v[120:123], v[56:59]
	v_mfma_f32_16x16x32_bf16 v[60:63], v[92:95], v[124:127], v[60:63]
	s_waitcnt vmcnt(0)
	s_barrier
	s_add_u32 s26, s26, 0x80
	s_addc_u32 s27, s27, 0
	s_add_u32 s28, s28, 0x80
	s_addc_u32 s29, s29, 0
	s_mov_b32 m0, s7
	s_nop 0
	global_load_lds_dwordx4 v132, s[26:27] offset:0
	global_load_lds_dwordx4 v133, s[26:27] offset:1024
	global_load_lds_dwordx4 v134, s[26:27] offset:2048
	global_load_lds_dwordx4 v135, s[26:27] offset:3072
	s_mov_b32 m0, s8
	s_nop 0
	global_load_lds_dwordx4 v132, s[28:29] offset:0
	global_load_lds_dwordx4 v133, s[28:29] offset:1024
	global_load_lds_dwordx4 v134, s[28:29] offset:2048
	global_load_lds_dwordx4 v135, s[28:29] offset:3072
	ds_read_b128 v[64:67], v136 offset:0
	ds_read_b128 v[96:99], v140 offset:0
	ds_read_b128 v[100:103], v140 offset:2048
	ds_read_b128 v[104:107], v140 offset:4096
	ds_read_b128 v[108:111], v140 offset:6144
	ds_read_b128 v[68:71], v136 offset:2048
	ds_read_b128 v[72:75], v136 offset:4096
	ds_read_b128 v[76:79], v136 offset:6144
	s_waitcnt lgkmcnt(3)
	v_mfma_f32_16x16x32_bf16 v[0:3], v[64:67], v[96:99], v[0:3]
	v_mfma_f32_16x16x32_bf16 v[4:7], v[64:67], v[100:103], v[4:7]
	ds_read_b128 v[80:83], v137 offset:0
	v_mfma_f32_16x16x32_bf16 v[8:11], v[64:67], v[104:107], v[8:11]
	v_mfma_f32_16x16x32_bf16 v[12:15], v[64:67], v[108:111], v[12:15]
	ds_read_b128 v[112:115], v141 offset:0
	s_waitcnt lgkmcnt(4)
	v_mfma_f32_16x16x32_bf16 v[16:19], v[68:71], v[96:99], v[16:19]
	v_mfma_f32_16x16x32_bf16 v[20:23], v[68:71], v[100:103], v[20:23]
	ds_read_b128 v[116:119], v141 offset:2048
	v_mfma_f32_16x16x32_bf16 v[24:27], v[68:71], v[104:107], v[24:27]
	v_mfma_f32_16x16x32_bf16 v[28:31], v[68:71], v[108:111], v[28:31]
	ds_read_b128 v[120:123], v141 offset:4096
	s_waitcnt lgkmcnt(5)
	v_mfma_f32_16x16x32_bf16 v[32:35], v[72:75], v[96:99], v[32:35]
	v_mfma_f32_16x16x32_bf16 v[36:39], v[72:75], v[100:103], v[36:39]
	ds_read_b128 v[124:127], v141 offset:6144
	v_mfma_f32_16x16x32_bf16 v[40:43], v[72:75], v[104:107], v[40:43]
	v_mfma_f32_16x16x32_bf16 v[44:47], v[72:75], v[108:111], v[44:47]
	ds_read_b128 v[84:87], v137 offset:2048
	s_waitcnt lgkmcnt(6)
	v_mfma_f32_16x16x32_bf16 v[48:51], v[76:79], v[96:99], v[48:51]
	v_mfma_f32_16x16x32_bf16 v[52:55], v[76:79], v[100:103], v[52:55]
	ds_read_b128 v[88:91], v137 offset:4096
	v_mfma_f32_16x16x32_bf16 v[56:59], v[76:79], v[104:107], v[56:59]
	v_mfma_f32_16x16x32_bf16 v[60:63], v[76:79], v[108:111], v[60:63]
	ds_read_b128 v[92:95], v137 offset:6144
	s_waitcnt lgkmcnt(3)
	v_mfma_f32_16x16x32_bf16 v[0:3], v[80:83], v[112:115], v[0:3]
	v_mfma_f32_16x16x32_bf16 v[4:7], v[80:83], v[116:119], v[4:7]
	v_mfma_f32_16x16x32_bf16 v[8:11], v[80:83], v[120:123], v[8:11]
	v_mfma_f32_16x16x32_bf16 v[12:15], v[80:83], v[124:127], v[12:15]
	s_waitcnt lgkmcnt(2)
	v_mfma_f32_16x16x32_bf16 v[16:19], v[84:87], v[112:115], v[16:19]
	v_mfma_f32_16x16x32_bf16 v[20:23], v[84:87], v[116:119], v[20:23]
	v_mfma_f32_16x16x32_bf16 v[24:27], v[84:87], v[120:123], v[24:27]
	v_mfma_f32_16x16x32_bf16 v[28:31], v[84:87], v[124:127], v[28:31]
	s_waitcnt lgkmcnt(1)
	v_mfma_f32_16x16x32_bf16 v[32:35], v[88:91], v[112:115], v[32:35]
	v_mfma_f32_16x16x32_bf16 v[36:39], v[88:91], v[116:119], v[36:39]
	v_mfma_f32_16x16x32_bf16 v[40:43], v[88:91], v[120:123], v[40:43]
	v_mfma_f32_16x16x32_bf16 v[44:47], v[88:91], v[124:127], v[44:47]
	s_waitcnt lgkmcnt(0)
	v_mfma_f32_16x16x32_bf16 v[48:51], v[92:95], v[112:115], v[48:51]
	v_mfma_f32_16x16x32_bf16 v[52:55], v[92:95], v[116:119], v[52:55]
	v_mfma_f32_16x16x32_bf16 v[56:59], v[92:95], v[120:123], v[56:59]
	v_mfma_f32_16x16x32_bf16 v[60:63], v[92:95], v[124:127], v[60:63]
	s_waitcnt vmcnt(0)
	s_barrier
	s_add_u32 s26, s26, 0x80
	s_addc_u32 s27, s27, 0
	s_add_u32 s28, s28, 0x80
	s_addc_u32 s29, s29, 0
	s_mov_b32 m0, s5
	s_nop 0
	global_load_lds_dwordx4 v132, s[26:27] offset:0
	global_load_lds_dwordx4 v133, s[26:27] offset:1024
	global_load_lds_dwordx4 v134, s[26:27] offset:2048
	global_load_lds_dwordx4 v135, s[26:27] offset:3072
	s_mov_b32 m0, s6
	s_nop 0
	global_load_lds_dwordx4 v132, s[28:29] offset:0
	global_load_lds_dwordx4 v133, s[28:29] offset:1024
	global_load_lds_dwordx4 v134, s[28:29] offset:2048
	global_load_lds_dwordx4 v135, s[28:29] offset:3072
	ds_read_b128 v[64:67], v138 offset:0
	ds_read_b128 v[96:99], v142 offset:0
	ds_read_b128 v[100:103], v142 offset:2048
	ds_read_b128 v[104:107], v142 offset:4096
	ds_read_b128 v[108:111], v142 offset:6144
	ds_read_b128 v[68:71], v138 offset:2048
	ds_read_b128 v[72:75], v138 offset:4096
	ds_read_b128 v[76:79], v138 offset:6144
	s_waitcnt lgkmcnt(3)
	v_mfma_f32_16x16x32_bf16 v[0:3], v[64:67], v[96:99], v[0:3]
	v_mfma_f32_16x16x32_bf16 v[4:7], v[64:67], v[100:103], v[4:7]
	ds_read_b128 v[80:83], v139 offset:0
	v_mfma_f32_16x16x32_bf16 v[8:11], v[64:67], v[104:107], v[8:11]
	v_mfma_f32_16x16x32_bf16 v[12:15], v[64:67], v[108:111], v[12:15]
	ds_read_b128 v[112:115], v143 offset:0
	s_waitcnt lgkmcnt(4)
	v_mfma_f32_16x16x32_bf16 v[16:19], v[68:71], v[96:99], v[16:19]
	v_mfma_f32_16x16x32_bf16 v[20:23], v[68:71], v[100:103], v[20:23]
	ds_read_b128 v[116:119], v143 offset:2048
	v_mfma_f32_16x16x32_bf16 v[24:27], v[68:71], v[104:107], v[24:27]
	v_mfma_f32_16x16x32_bf16 v[28:31], v[68:71], v[108:111], v[28:31]
	ds_read_b128 v[120:123], v143 offset:4096
	s_waitcnt lgkmcnt(5)
	v_mfma_f32_16x16x32_bf16 v[32:35], v[72:75], v[96:99], v[32:35]
	v_mfma_f32_16x16x32_bf16 v[36:39], v[72:75], v[100:103], v[36:39]
	ds_read_b128 v[124:127], v143 offset:6144
	v_mfma_f32_16x16x32_bf16 v[40:43], v[72:75], v[104:107], v[40:43]
	v_mfma_f32_16x16x32_bf16 v[44:47], v[72:75], v[108:111], v[44:47]
	ds_read_b128 v[84:87], v139 offset:2048
	s_waitcnt lgkmcnt(6)
	v_mfma_f32_16x16x32_bf16 v[48:51], v[76:79], v[96:99], v[48:51]
	v_mfma_f32_16x16x32_bf16 v[52:55], v[76:79], v[100:103], v[52:55]
	ds_read_b128 v[88:91], v139 offset:4096
	v_mfma_f32_16x16x32_bf16 v[56:59], v[76:79], v[104:107], v[56:59]
	v_mfma_f32_16x16x32_bf16 v[60:63], v[76:79], v[108:111], v[60:63]
	ds_read_b128 v[92:95], v139 offset:6144
	s_waitcnt lgkmcnt(3)
	v_mfma_f32_16x16x32_bf16 v[0:3], v[80:83], v[112:115], v[0:3]
	v_mfma_f32_16x16x32_bf16 v[4:7], v[80:83], v[116:119], v[4:7]
	v_mfma_f32_16x16x32_bf16 v[8:11], v[80:83], v[120:123], v[8:11]
	v_mfma_f32_16x16x32_bf16 v[12:15], v[80:83], v[124:127], v[12:15]
	s_waitcnt lgkmcnt(2)
	v_mfma_f32_16x16x32_bf16 v[16:19], v[84:87], v[112:115], v[16:19]
	v_mfma_f32_16x16x32_bf16 v[20:23], v[84:87], v[116:119], v[20:23]
	v_mfma_f32_16x16x32_bf16 v[24:27], v[84:87], v[120:123], v[24:27]
	v_mfma_f32_16x16x32_bf16 v[28:31], v[84:87], v[124:127], v[28:31]
	s_waitcnt lgkmcnt(1)
	v_mfma_f32_16x16x32_bf16 v[32:35], v[88:91], v[112:115], v[32:35]
	v_mfma_f32_16x16x32_bf16 v[36:39], v[88:91], v[116:119], v[36:39]
	v_mfma_f32_16x16x32_bf16 v[40:43], v[88:91], v[120:123], v[40:43]
	v_mfma_f32_16x16x32_bf16 v[44:47], v[88:91], v[124:127], v[44:47]
	s_waitcnt lgkmcnt(0)
	v_mfma_f32_16x16x32_bf16 v[48:51], v[92:95], v[112:115], v[48:51]
	v_mfma_f32_16x16x32_bf16 v[52:55], v[92:95], v[116:119], v[52:55]
	v_mfma_f32_16x16x32_bf16 v[56:59], v[92:95], v[120:123], v[56:59]
	v_mfma_f32_16x16x32_bf16 v[60:63], v[92:95], v[124:127], v[60:63]
	s_waitcnt vmcnt(0)
	s_barrier
	s_add_u32 s26, s26, 0x80
	s_addc_u32 s27, s27, 0
	s_add_u32 s28, s28, 0x80
	s_addc_u32 s29, s29, 0
	s_mov_b32 m0, s7
	s_nop 0
	global_load_lds_dwordx4 v132, s[26:27] offset:0
	global_load_lds_dwordx4 v133, s[26:27] offset:1024
	global_load_lds_dwordx4 v134, s[26:27] offset:2048
	global_load_lds_dwordx4 v135, s[26:27] offset:3072
	s_mov_b32 m0, s8
	s_nop 0
	global_load_lds_dwordx4 v132, s[28:29] offset:0
	global_load_lds_dwordx4 v133, s[28:29] offset:1024
	global_load_lds_dwordx4 v134, s[28:29] offset:2048
	global_load_lds_dwordx4 v135, s[28:29] offset:3072
	ds_read_b128 v[64:67], v136 offset:0
	ds_read_b128 v[96:99], v140 offset:0
	ds_read_b128 v[100:103], v140 offset:2048
	ds_read_b128 v[104:107], v140 offset:4096
	ds_read_b128 v[108:111], v140 offset:6144
	ds_read_b128 v[68:71], v136 offset:2048
	ds_read_b128 v[72:75], v136 offset:4096
	ds_read_b128 v[76:79], v136 offset:6144
	s_waitcnt lgkmcnt(3)
	v_mfma_f32_16x16x32_bf16 v[0:3], v[64:67], v[96:99], v[0:3]
	v_mfma_f32_16x16x32_bf16 v[4:7], v[64:67], v[100:103], v[4:7]
	ds_read_b128 v[80:83], v137 offset:0
	v_mfma_f32_16x16x32_bf16 v[8:11], v[64:67], v[104:107], v[8:11]
	v_mfma_f32_16x16x32_bf16 v[12:15], v[64:67], v[108:111], v[12:15]
	ds_read_b128 v[112:115], v141 offset:0
	s_waitcnt lgkmcnt(4)
	v_mfma_f32_16x16x32_bf16 v[16:19], v[68:71], v[96:99], v[16:19]
	v_mfma_f32_16x16x32_bf16 v[20:23], v[68:71], v[100:103], v[20:23]
	ds_read_b128 v[116:119], v141 offset:2048
	v_mfma_f32_16x16x32_bf16 v[24:27], v[68:71], v[104:107], v[24:27]
	v_mfma_f32_16x16x32_bf16 v[28:31], v[68:71], v[108:111], v[28:31]
	ds_read_b128 v[120:123], v141 offset:4096
	s_waitcnt lgkmcnt(5)
	v_mfma_f32_16x16x32_bf16 v[32:35], v[72:75], v[96:99], v[32:35]
	v_mfma_f32_16x16x32_bf16 v[36:39], v[72:75], v[100:103], v[36:39]
	ds_read_b128 v[124:127], v141 offset:6144
	v_mfma_f32_16x16x32_bf16 v[40:43], v[72:75], v[104:107], v[40:43]
	v_mfma_f32_16x16x32_bf16 v[44:47], v[72:75], v[108:111], v[44:47]
	ds_read_b128 v[84:87], v137 offset:2048
	s_waitcnt lgkmcnt(6)
	v_mfma_f32_16x16x32_bf16 v[48:51], v[76:79], v[96:99], v[48:51]
	v_mfma_f32_16x16x32_bf16 v[52:55], v[76:79], v[100:103], v[52:55]
	ds_read_b128 v[88:91], v137 offset:4096
	v_mfma_f32_16x16x32_bf16 v[56:59], v[76:79], v[104:107], v[56:59]
	v_mfma_f32_16x16x32_bf16 v[60:63], v[76:79], v[108:111], v[60:63]
	ds_read_b128 v[92:95], v137 offset:6144
	s_waitcnt lgkmcnt(3)
	v_mfma_f32_16x16x32_bf16 v[0:3], v[80:83], v[112:115], v[0:3]
	v_mfma_f32_16x16x32_bf16 v[4:7], v[80:83], v[116:119], v[4:7]
	v_mfma_f32_16x16x32_bf16 v[8:11], v[80:83], v[120:123], v[8:11]
	v_mfma_f32_16x16x32_bf16 v[12:15], v[80:83], v[124:127], v[12:15]
	s_waitcnt lgkmcnt(2)
	v_mfma_f32_16x16x32_bf16 v[16:19], v[84:87], v[112:115], v[16:19]
	v_mfma_f32_16x16x32_bf16 v[20:23], v[84:87], v[116:119], v[20:23]
	v_mfma_f32_16x16x32_bf16 v[24:27], v[84:87], v[120:123], v[24:27]
	v_mfma_f32_16x16x32_bf16 v[28:31], v[84:87], v[124:127], v[28:31]
	s_waitcnt lgkmcnt(1)
	v_mfma_f32_16x16x32_bf16 v[32:35], v[88:91], v[112:115], v[32:35]
	v_mfma_f32_16x16x32_bf16 v[36:39], v[88:91], v[116:119], v[36:39]
	v_mfma_f32_16x16x32_bf16 v[40:43], v[88:91], v[120:123], v[40:43]
	v_mfma_f32_16x16x32_bf16 v[44:47], v[88:91], v[124:127], v[44:47]
	s_waitcnt lgkmcnt(0)
	v_mfma_f32_16x16x32_bf16 v[48:51], v[92:95], v[112:115], v[48:51]
	v_mfma_f32_16x16x32_bf16 v[52:55], v[92:95], v[116:119], v[52:55]
	v_mfma_f32_16x16x32_bf16 v[56:59], v[92:95], v[120:123], v[56:59]
	v_mfma_f32_16x16x32_bf16 v[60:63], v[92:95], v[124:127], v[60:63]
	s_waitcnt vmcnt(0)
	s_barrier
	s_add_u32 s26, s26, 0x80
	s_addc_u32 s27, s27, 0
	s_add_u32 s28, s28, 0x80
	s_addc_u32 s29, s29, 0
	s_mov_b32 m0, s5
	s_nop 0
	global_load_lds_dwordx4 v132, s[26:27] offset:0
	global_load_lds_dwordx4 v133, s[26:27] offset:1024
	global_load_lds_dwordx4 v134, s[26:27] offset:2048
	global_load_lds_dwordx4 v135, s[26:27] offset:3072
	s_mov_b32 m0, s6
	s_nop 0
	global_load_lds_dwordx4 v132, s[28:29] offset:0
	global_load_lds_dwordx4 v133, s[28:29] offset:1024
	global_load_lds_dwordx4 v134, s[28:29] offset:2048
	global_load_lds_dwordx4 v135, s[28:29] offset:3072
	ds_read_b128 v[64:67], v138 offset:0
	ds_read_b128 v[96:99], v142 offset:0
	ds_read_b128 v[100:103], v142 offset:2048
	ds_read_b128 v[104:107], v142 offset:4096
	ds_read_b128 v[108:111], v142 offset:6144
	ds_read_b128 v[68:71], v138 offset:2048
	ds_read_b128 v[72:75], v138 offset:4096
	ds_read_b128 v[76:79], v138 offset:6144
	s_waitcnt lgkmcnt(3)
	v_mfma_f32_16x16x32_bf16 v[0:3], v[64:67], v[96:99], v[0:3]
	v_mfma_f32_16x16x32_bf16 v[4:7], v[64:67], v[100:103], v[4:7]
	ds_read_b128 v[80:83], v139 offset:0
	v_mfma_f32_16x16x32_bf16 v[8:11], v[64:67], v[104:107], v[8:11]
	v_mfma_f32_16x16x32_bf16 v[12:15], v[64:67], v[108:111], v[12:15]
	ds_read_b128 v[112:115], v143 offset:0
	s_waitcnt lgkmcnt(4)
	v_mfma_f32_16x16x32_bf16 v[16:19], v[68:71], v[96:99], v[16:19]
	v_mfma_f32_16x16x32_bf16 v[20:23], v[68:71], v[100:103], v[20:23]
	ds_read_b128 v[116:119], v143 offset:2048
	v_mfma_f32_16x16x32_bf16 v[24:27], v[68:71], v[104:107], v[24:27]
	v_mfma_f32_16x16x32_bf16 v[28:31], v[68:71], v[108:111], v[28:31]
	ds_read_b128 v[120:123], v143 offset:4096
	s_waitcnt lgkmcnt(5)
	v_mfma_f32_16x16x32_bf16 v[32:35], v[72:75], v[96:99], v[32:35]
	v_mfma_f32_16x16x32_bf16 v[36:39], v[72:75], v[100:103], v[36:39]
	ds_read_b128 v[124:127], v143 offset:6144
	v_mfma_f32_16x16x32_bf16 v[40:43], v[72:75], v[104:107], v[40:43]
	v_mfma_f32_16x16x32_bf16 v[44:47], v[72:75], v[108:111], v[44:47]
	ds_read_b128 v[84:87], v139 offset:2048
	s_waitcnt lgkmcnt(6)
	v_mfma_f32_16x16x32_bf16 v[48:51], v[76:79], v[96:99], v[48:51]
	v_mfma_f32_16x16x32_bf16 v[52:55], v[76:79], v[100:103], v[52:55]
	ds_read_b128 v[88:91], v139 offset:4096
	v_mfma_f32_16x16x32_bf16 v[56:59], v[76:79], v[104:107], v[56:59]
	v_mfma_f32_16x16x32_bf16 v[60:63], v[76:79], v[108:111], v[60:63]
	ds_read_b128 v[92:95], v139 offset:6144
	s_waitcnt lgkmcnt(3)
	v_mfma_f32_16x16x32_bf16 v[0:3], v[80:83], v[112:115], v[0:3]
	v_mfma_f32_16x16x32_bf16 v[4:7], v[80:83], v[116:119], v[4:7]
	v_mfma_f32_16x16x32_bf16 v[8:11], v[80:83], v[120:123], v[8:11]
	v_mfma_f32_16x16x32_bf16 v[12:15], v[80:83], v[124:127], v[12:15]
	s_waitcnt lgkmcnt(2)
	v_mfma_f32_16x16x32_bf16 v[16:19], v[84:87], v[112:115], v[16:19]
	v_mfma_f32_16x16x32_bf16 v[20:23], v[84:87], v[116:119], v[20:23]
	v_mfma_f32_16x16x32_bf16 v[24:27], v[84:87], v[120:123], v[24:27]
	v_mfma_f32_16x16x32_bf16 v[28:31], v[84:87], v[124:127], v[28:31]
	s_waitcnt lgkmcnt(1)
	v_mfma_f32_16x16x32_bf16 v[32:35], v[88:91], v[112:115], v[32:35]
	v_mfma_f32_16x16x32_bf16 v[36:39], v[88:91], v[116:119], v[36:39]
	v_mfma_f32_16x16x32_bf16 v[40:43], v[88:91], v[120:123], v[40:43]
	v_mfma_f32_16x16x32_bf16 v[44:47], v[88:91], v[124:127], v[44:47]
	s_waitcnt lgkmcnt(0)
	v_mfma_f32_16x16x32_bf16 v[48:51], v[92:95], v[112:115], v[48:51]
	v_mfma_f32_16x16x32_bf16 v[52:55], v[92:95], v[116:119], v[52:55]
	v_mfma_f32_16x16x32_bf16 v[56:59], v[92:95], v[120:123], v[56:59]
	v_mfma_f32_16x16x32_bf16 v[60:63], v[92:95], v[124:127], v[60:63]
	s_waitcnt vmcnt(0)
	s_barrier
	s_add_u32 s26, s26, 0x80
	s_addc_u32 s27, s27, 0
	s_add_u32 s28, s28, 0x80
	s_addc_u32 s29, s29, 0
	s_mov_b32 m0, s7
	s_nop 0
	global_load_lds_dwordx4 v132, s[26:27] offset:0
	global_load_lds_dwordx4 v133, s[26:27] offset:1024
	global_load_lds_dwordx4 v134, s[26:27] offset:2048
	global_load_lds_dwordx4 v135, s[26:27] offset:3072
	s_mov_b32 m0, s8
	s_nop 0
	global_load_lds_dwordx4 v132, s[28:29] offset:0
	global_load_lds_dwordx4 v133, s[28:29] offset:1024
	global_load_lds_dwordx4 v134, s[28:29] offset:2048
	global_load_lds_dwordx4 v135, s[28:29] offset:3072
	ds_read_b128 v[64:67], v136 offset:0
	ds_read_b128 v[96:99], v140 offset:0
	ds_read_b128 v[100:103], v140 offset:2048
	ds_read_b128 v[104:107], v140 offset:4096
	ds_read_b128 v[108:111], v140 offset:6144
	ds_read_b128 v[68:71], v136 offset:2048
	ds_read_b128 v[72:75], v136 offset:4096
	ds_read_b128 v[76:79], v136 offset:6144
	s_waitcnt lgkmcnt(3)
	v_mfma_f32_16x16x32_bf16 v[0:3], v[64:67], v[96:99], v[0:3]
	v_mfma_f32_16x16x32_bf16 v[4:7], v[64:67], v[100:103], v[4:7]
	ds_read_b128 v[80:83], v137 offset:0
	v_mfma_f32_16x16x32_bf16 v[8:11], v[64:67], v[104:107], v[8:11]
	v_mfma_f32_16x16x32_bf16 v[12:15], v[64:67], v[108:111], v[12:15]
	ds_read_b128 v[112:115], v141 offset:0
	s_waitcnt lgkmcnt(4)
	v_mfma_f32_16x16x32_bf16 v[16:19], v[68:71], v[96:99], v[16:19]
	v_mfma_f32_16x16x32_bf16 v[20:23], v[68:71], v[100:103], v[20:23]
	ds_read_b128 v[116:119], v141 offset:2048
	v_mfma_f32_16x16x32_bf16 v[24:27], v[68:71], v[104:107], v[24:27]
	v_mfma_f32_16x16x32_bf16 v[28:31], v[68:71], v[108:111], v[28:31]
	ds_read_b128 v[120:123], v141 offset:4096
	s_waitcnt lgkmcnt(5)
	v_mfma_f32_16x16x32_bf16 v[32:35], v[72:75], v[96:99], v[32:35]
	v_mfma_f32_16x16x32_bf16 v[36:39], v[72:75], v[100:103], v[36:39]
	ds_read_b128 v[124:127], v141 offset:6144
	v_mfma_f32_16x16x32_bf16 v[40:43], v[72:75], v[104:107], v[40:43]
	v_mfma_f32_16x16x32_bf16 v[44:47], v[72:75], v[108:111], v[44:47]
	ds_read_b128 v[84:87], v137 offset:2048
	s_waitcnt lgkmcnt(6)
	v_mfma_f32_16x16x32_bf16 v[48:51], v[76:79], v[96:99], v[48:51]
	v_mfma_f32_16x16x32_bf16 v[52:55], v[76:79], v[100:103], v[52:55]
	ds_read_b128 v[88:91], v137 offset:4096
	v_mfma_f32_16x16x32_bf16 v[56:59], v[76:79], v[104:107], v[56:59]
	v_mfma_f32_16x16x32_bf16 v[60:63], v[76:79], v[108:111], v[60:63]
	ds_read_b128 v[92:95], v137 offset:6144
	s_waitcnt lgkmcnt(3)
	v_mfma_f32_16x16x32_bf16 v[0:3], v[80:83], v[112:115], v[0:3]
	v_mfma_f32_16x16x32_bf16 v[4:7], v[80:83], v[116:119], v[4:7]
	v_mfma_f32_16x16x32_bf16 v[8:11], v[80:83], v[120:123], v[8:11]
	v_mfma_f32_16x16x32_bf16 v[12:15], v[80:83], v[124:127], v[12:15]
	s_waitcnt lgkmcnt(2)
	v_mfma_f32_16x16x32_bf16 v[16:19], v[84:87], v[112:115], v[16:19]
	v_mfma_f32_16x16x32_bf16 v[20:23], v[84:87], v[116:119], v[20:23]
	v_mfma_f32_16x16x32_bf16 v[24:27], v[84:87], v[120:123], v[24:27]
	v_mfma_f32_16x16x32_bf16 v[28:31], v[84:87], v[124:127], v[28:31]
	s_waitcnt lgkmcnt(1)
	v_mfma_f32_16x16x32_bf16 v[32:35], v[88:91], v[112:115], v[32:35]
	v_mfma_f32_16x16x32_bf16 v[36:39], v[88:91], v[116:119], v[36:39]
	v_mfma_f32_16x16x32_bf16 v[40:43], v[88:91], v[120:123], v[40:43]
	v_mfma_f32_16x16x32_bf16 v[44:47], v[88:91], v[124:127], v[44:47]
	s_waitcnt lgkmcnt(0)
	v_mfma_f32_16x16x32_bf16 v[48:51], v[92:95], v[112:115], v[48:51]
	v_mfma_f32_16x16x32_bf16 v[52:55], v[92:95], v[116:119], v[52:55]
	v_mfma_f32_16x16x32_bf16 v[56:59], v[92:95], v[120:123], v[56:59]
	v_mfma_f32_16x16x32_bf16 v[60:63], v[92:95], v[124:127], v[60:63]
	s_waitcnt vmcnt(0)
	s_barrier
	s_add_u32 s26, s26, 0x80
	s_addc_u32 s27, s27, 0
	s_add_u32 s28, s28, 0x80
	s_addc_u32 s29, s29, 0
	s_mov_b32 m0, s5
	s_nop 0
	global_load_lds_dwordx4 v132, s[26:27] offset:0
	global_load_lds_dwordx4 v133, s[26:27] offset:1024
	global_load_lds_dwordx4 v134, s[26:27] offset:2048
	global_load_lds_dwordx4 v135, s[26:27] offset:3072
	s_mov_b32 m0, s6
	s_nop 0
	global_load_lds_dwordx4 v132, s[28:29] offset:0
	global_load_lds_dwordx4 v133, s[28:29] offset:1024
	global_load_lds_dwordx4 v134, s[28:29] offset:2048
	global_load_lds_dwordx4 v135, s[28:29] offset:3072
	ds_read_b128 v[64:67], v138 offset:0
	ds_read_b128 v[96:99], v142 offset:0
	ds_read_b128 v[100:103], v142 offset:2048
	ds_read_b128 v[104:107], v142 offset:4096
	ds_read_b128 v[108:111], v142 offset:6144
	ds_read_b128 v[68:71], v138 offset:2048
	ds_read_b128 v[72:75], v138 offset:4096
	ds_read_b128 v[76:79], v138 offset:6144
	s_waitcnt lgkmcnt(3)
	v_mfma_f32_16x16x32_bf16 v[0:3], v[64:67], v[96:99], v[0:3]
	v_mfma_f32_16x16x32_bf16 v[4:7], v[64:67], v[100:103], v[4:7]
	ds_read_b128 v[80:83], v139 offset:0
	v_mfma_f32_16x16x32_bf16 v[8:11], v[64:67], v[104:107], v[8:11]
	v_mfma_f32_16x16x32_bf16 v[12:15], v[64:67], v[108:111], v[12:15]
	ds_read_b128 v[112:115], v143 offset:0
	s_waitcnt lgkmcnt(4)
	v_mfma_f32_16x16x32_bf16 v[16:19], v[68:71], v[96:99], v[16:19]
	v_mfma_f32_16x16x32_bf16 v[20:23], v[68:71], v[100:103], v[20:23]
	ds_read_b128 v[116:119], v143 offset:2048
	v_mfma_f32_16x16x32_bf16 v[24:27], v[68:71], v[104:107], v[24:27]
	v_mfma_f32_16x16x32_bf16 v[28:31], v[68:71], v[108:111], v[28:31]
	ds_read_b128 v[120:123], v143 offset:4096
	s_waitcnt lgkmcnt(5)
	v_mfma_f32_16x16x32_bf16 v[32:35], v[72:75], v[96:99], v[32:35]
	v_mfma_f32_16x16x32_bf16 v[36:39], v[72:75], v[100:103], v[36:39]
	ds_read_b128 v[124:127], v143 offset:6144
	v_mfma_f32_16x16x32_bf16 v[40:43], v[72:75], v[104:107], v[40:43]
	v_mfma_f32_16x16x32_bf16 v[44:47], v[72:75], v[108:111], v[44:47]
	ds_read_b128 v[84:87], v139 offset:2048
	s_waitcnt lgkmcnt(6)
	v_mfma_f32_16x16x32_bf16 v[48:51], v[76:79], v[96:99], v[48:51]
	v_mfma_f32_16x16x32_bf16 v[52:55], v[76:79], v[100:103], v[52:55]
	ds_read_b128 v[88:91], v139 offset:4096
	v_mfma_f32_16x16x32_bf16 v[56:59], v[76:79], v[104:107], v[56:59]
	v_mfma_f32_16x16x32_bf16 v[60:63], v[76:79], v[108:111], v[60:63]
	ds_read_b128 v[92:95], v139 offset:6144
	s_waitcnt lgkmcnt(3)
	v_mfma_f32_16x16x32_bf16 v[0:3], v[80:83], v[112:115], v[0:3]
	v_mfma_f32_16x16x32_bf16 v[4:7], v[80:83], v[116:119], v[4:7]
	v_mfma_f32_16x16x32_bf16 v[8:11], v[80:83], v[120:123], v[8:11]
	v_mfma_f32_16x16x32_bf16 v[12:15], v[80:83], v[124:127], v[12:15]
	s_waitcnt lgkmcnt(2)
	v_mfma_f32_16x16x32_bf16 v[16:19], v[84:87], v[112:115], v[16:19]
	v_mfma_f32_16x16x32_bf16 v[20:23], v[84:87], v[116:119], v[20:23]
	v_mfma_f32_16x16x32_bf16 v[24:27], v[84:87], v[120:123], v[24:27]
	v_mfma_f32_16x16x32_bf16 v[28:31], v[84:87], v[124:127], v[28:31]
	s_waitcnt lgkmcnt(1)
	v_mfma_f32_16x16x32_bf16 v[32:35], v[88:91], v[112:115], v[32:35]
	v_mfma_f32_16x16x32_bf16 v[36:39], v[88:91], v[116:119], v[36:39]
	v_mfma_f32_16x16x32_bf16 v[40:43], v[88:91], v[120:123], v[40:43]
	v_mfma_f32_16x16x32_bf16 v[44:47], v[88:91], v[124:127], v[44:47]
	s_waitcnt lgkmcnt(0)
	v_mfma_f32_16x16x32_bf16 v[48:51], v[92:95], v[112:115], v[48:51]
	v_mfma_f32_16x16x32_bf16 v[52:55], v[92:95], v[116:119], v[52:55]
	v_mfma_f32_16x16x32_bf16 v[56:59], v[92:95], v[120:123], v[56:59]
	v_mfma_f32_16x16x32_bf16 v[60:63], v[92:95], v[124:127], v[60:63]
	s_waitcnt vmcnt(0)
	s_barrier
	s_add_u32 s26, s26, 0x80
	s_addc_u32 s27, s27, 0
	s_add_u32 s28, s28, 0x80
	s_addc_u32 s29, s29, 0
	s_mov_b32 m0, s7
	s_nop 0
	global_load_lds_dwordx4 v132, s[26:27] offset:0
	global_load_lds_dwordx4 v133, s[26:27] offset:1024
	global_load_lds_dwordx4 v134, s[26:27] offset:2048
	global_load_lds_dwordx4 v135, s[26:27] offset:3072
	s_mov_b32 m0, s8
	s_nop 0
	global_load_lds_dwordx4 v132, s[28:29] offset:0
	global_load_lds_dwordx4 v133, s[28:29] offset:1024
	global_load_lds_dwordx4 v134, s[28:29] offset:2048
	global_load_lds_dwordx4 v135, s[28:29] offset:3072
	ds_read_b128 v[64:67], v136 offset:0
	ds_read_b128 v[96:99], v140 offset:0
	ds_read_b128 v[100:103], v140 offset:2048
	ds_read_b128 v[104:107], v140 offset:4096
	ds_read_b128 v[108:111], v140 offset:6144
	ds_read_b128 v[68:71], v136 offset:2048
	ds_read_b128 v[72:75], v136 offset:4096
	ds_read_b128 v[76:79], v136 offset:6144
	s_waitcnt lgkmcnt(3)
	v_mfma_f32_16x16x32_bf16 v[0:3], v[64:67], v[96:99], v[0:3]
	v_mfma_f32_16x16x32_bf16 v[4:7], v[64:67], v[100:103], v[4:7]
	ds_read_b128 v[80:83], v137 offset:0
	v_mfma_f32_16x16x32_bf16 v[8:11], v[64:67], v[104:107], v[8:11]
	v_mfma_f32_16x16x32_bf16 v[12:15], v[64:67], v[108:111], v[12:15]
	ds_read_b128 v[112:115], v141 offset:0
	s_waitcnt lgkmcnt(4)
	v_mfma_f32_16x16x32_bf16 v[16:19], v[68:71], v[96:99], v[16:19]
	v_mfma_f32_16x16x32_bf16 v[20:23], v[68:71], v[100:103], v[20:23]
	ds_read_b128 v[116:119], v141 offset:2048
	v_mfma_f32_16x16x32_bf16 v[24:27], v[68:71], v[104:107], v[24:27]
	v_mfma_f32_16x16x32_bf16 v[28:31], v[68:71], v[108:111], v[28:31]
	ds_read_b128 v[120:123], v141 offset:4096
	s_waitcnt lgkmcnt(5)
	v_mfma_f32_16x16x32_bf16 v[32:35], v[72:75], v[96:99], v[32:35]
	v_mfma_f32_16x16x32_bf16 v[36:39], v[72:75], v[100:103], v[36:39]
	ds_read_b128 v[124:127], v141 offset:6144
	v_mfma_f32_16x16x32_bf16 v[40:43], v[72:75], v[104:107], v[40:43]
	v_mfma_f32_16x16x32_bf16 v[44:47], v[72:75], v[108:111], v[44:47]
	ds_read_b128 v[84:87], v137 offset:2048
	s_waitcnt lgkmcnt(6)
	v_mfma_f32_16x16x32_bf16 v[48:51], v[76:79], v[96:99], v[48:51]
	v_mfma_f32_16x16x32_bf16 v[52:55], v[76:79], v[100:103], v[52:55]
	ds_read_b128 v[88:91], v137 offset:4096
	v_mfma_f32_16x16x32_bf16 v[56:59], v[76:79], v[104:107], v[56:59]
	v_mfma_f32_16x16x32_bf16 v[60:63], v[76:79], v[108:111], v[60:63]
	ds_read_b128 v[92:95], v137 offset:6144
	s_waitcnt lgkmcnt(3)
	v_mfma_f32_16x16x32_bf16 v[0:3], v[80:83], v[112:115], v[0:3]
	v_mfma_f32_16x16x32_bf16 v[4:7], v[80:83], v[116:119], v[4:7]
	v_mfma_f32_16x16x32_bf16 v[8:11], v[80:83], v[120:123], v[8:11]
	v_mfma_f32_16x16x32_bf16 v[12:15], v[80:83], v[124:127], v[12:15]
	s_waitcnt lgkmcnt(2)
	v_mfma_f32_16x16x32_bf16 v[16:19], v[84:87], v[112:115], v[16:19]
	v_mfma_f32_16x16x32_bf16 v[20:23], v[84:87], v[116:119], v[20:23]
	v_mfma_f32_16x16x32_bf16 v[24:27], v[84:87], v[120:123], v[24:27]
	v_mfma_f32_16x16x32_bf16 v[28:31], v[84:87], v[124:127], v[28:31]
	s_waitcnt lgkmcnt(1)
	v_mfma_f32_16x16x32_bf16 v[32:35], v[88:91], v[112:115], v[32:35]
	v_mfma_f32_16x16x32_bf16 v[36:39], v[88:91], v[116:119], v[36:39]
	v_mfma_f32_16x16x32_bf16 v[40:43], v[88:91], v[120:123], v[40:43]
	v_mfma_f32_16x16x32_bf16 v[44:47], v[88:91], v[124:127], v[44:47]
	s_waitcnt lgkmcnt(0)
	v_mfma_f32_16x16x32_bf16 v[48:51], v[92:95], v[112:115], v[48:51]
	v_mfma_f32_16x16x32_bf16 v[52:55], v[92:95], v[116:119], v[52:55]
	v_mfma_f32_16x16x32_bf16 v[56:59], v[92:95], v[120:123], v[56:59]
	v_mfma_f32_16x16x32_bf16 v[60:63], v[92:95], v[124:127], v[60:63]
	s_waitcnt vmcnt(0)
	s_barrier
	s_add_u32 s26, s26, 0x80
	s_addc_u32 s27, s27, 0
	s_add_u32 s28, s28, 0x80
	s_addc_u32 s29, s29, 0
	s_mov_b32 m0, s5
	s_nop 0
	global_load_lds_dwordx4 v132, s[26:27] offset:0
	global_load_lds_dwordx4 v133, s[26:27] offset:1024
	global_load_lds_dwordx4 v134, s[26:27] offset:2048
	global_load_lds_dwordx4 v135, s[26:27] offset:3072
	s_mov_b32 m0, s6
	s_nop 0
	global_load_lds_dwordx4 v132, s[28:29] offset:0
	global_load_lds_dwordx4 v133, s[28:29] offset:1024
	global_load_lds_dwordx4 v134, s[28:29] offset:2048
	global_load_lds_dwordx4 v135, s[28:29] offset:3072
	ds_read_b128 v[64:67], v138 offset:0
	ds_read_b128 v[96:99], v142 offset:0
	ds_read_b128 v[100:103], v142 offset:2048
	ds_read_b128 v[104:107], v142 offset:4096
	ds_read_b128 v[108:111], v142 offset:6144
	ds_read_b128 v[68:71], v138 offset:2048
	ds_read_b128 v[72:75], v138 offset:4096
	ds_read_b128 v[76:79], v138 offset:6144
	s_waitcnt lgkmcnt(3)
	v_mfma_f32_16x16x32_bf16 v[0:3], v[64:67], v[96:99], v[0:3]
	v_mfma_f32_16x16x32_bf16 v[4:7], v[64:67], v[100:103], v[4:7]
	ds_read_b128 v[80:83], v139 offset:0
	v_mfma_f32_16x16x32_bf16 v[8:11], v[64:67], v[104:107], v[8:11]
	v_mfma_f32_16x16x32_bf16 v[12:15], v[64:67], v[108:111], v[12:15]
	ds_read_b128 v[112:115], v143 offset:0
	s_waitcnt lgkmcnt(4)
	v_mfma_f32_16x16x32_bf16 v[16:19], v[68:71], v[96:99], v[16:19]
	v_mfma_f32_16x16x32_bf16 v[20:23], v[68:71], v[100:103], v[20:23]
	ds_read_b128 v[116:119], v143 offset:2048
	v_mfma_f32_16x16x32_bf16 v[24:27], v[68:71], v[104:107], v[24:27]
	v_mfma_f32_16x16x32_bf16 v[28:31], v[68:71], v[108:111], v[28:31]
	ds_read_b128 v[120:123], v143 offset:4096
	s_waitcnt lgkmcnt(5)
	v_mfma_f32_16x16x32_bf16 v[32:35], v[72:75], v[96:99], v[32:35]
	v_mfma_f32_16x16x32_bf16 v[36:39], v[72:75], v[100:103], v[36:39]
	ds_read_b128 v[124:127], v143 offset:6144
	v_mfma_f32_16x16x32_bf16 v[40:43], v[72:75], v[104:107], v[40:43]
	v_mfma_f32_16x16x32_bf16 v[44:47], v[72:75], v[108:111], v[44:47]
	ds_read_b128 v[84:87], v139 offset:2048
	s_waitcnt lgkmcnt(6)
	v_mfma_f32_16x16x32_bf16 v[48:51], v[76:79], v[96:99], v[48:51]
	v_mfma_f32_16x16x32_bf16 v[52:55], v[76:79], v[100:103], v[52:55]
	ds_read_b128 v[88:91], v139 offset:4096
	v_mfma_f32_16x16x32_bf16 v[56:59], v[76:79], v[104:107], v[56:59]
	v_mfma_f32_16x16x32_bf16 v[60:63], v[76:79], v[108:111], v[60:63]
	ds_read_b128 v[92:95], v139 offset:6144
	s_waitcnt lgkmcnt(3)
	v_mfma_f32_16x16x32_bf16 v[0:3], v[80:83], v[112:115], v[0:3]
	v_mfma_f32_16x16x32_bf16 v[4:7], v[80:83], v[116:119], v[4:7]
	v_mfma_f32_16x16x32_bf16 v[8:11], v[80:83], v[120:123], v[8:11]
	v_mfma_f32_16x16x32_bf16 v[12:15], v[80:83], v[124:127], v[12:15]
	s_waitcnt lgkmcnt(2)
	v_mfma_f32_16x16x32_bf16 v[16:19], v[84:87], v[112:115], v[16:19]
	v_mfma_f32_16x16x32_bf16 v[20:23], v[84:87], v[116:119], v[20:23]
	v_mfma_f32_16x16x32_bf16 v[24:27], v[84:87], v[120:123], v[24:27]
	v_mfma_f32_16x16x32_bf16 v[28:31], v[84:87], v[124:127], v[28:31]
	s_waitcnt lgkmcnt(1)
	v_mfma_f32_16x16x32_bf16 v[32:35], v[88:91], v[112:115], v[32:35]
	v_mfma_f32_16x16x32_bf16 v[36:39], v[88:91], v[116:119], v[36:39]
	v_mfma_f32_16x16x32_bf16 v[40:43], v[88:91], v[120:123], v[40:43]
	v_mfma_f32_16x16x32_bf16 v[44:47], v[88:91], v[124:127], v[44:47]
	s_waitcnt lgkmcnt(0)
	v_mfma_f32_16x16x32_bf16 v[48:51], v[92:95], v[112:115], v[48:51]
	v_mfma_f32_16x16x32_bf16 v[52:55], v[92:95], v[116:119], v[52:55]
	v_mfma_f32_16x16x32_bf16 v[56:59], v[92:95], v[120:123], v[56:59]
	v_mfma_f32_16x16x32_bf16 v[60:63], v[92:95], v[124:127], v[60:63]
	s_waitcnt vmcnt(0)
	s_barrier
	s_add_u32 s26, s26, 0x80
	s_addc_u32 s27, s27, 0
	s_add_u32 s28, s28, 0x80
	s_addc_u32 s29, s29, 0
	s_mov_b32 m0, s7
	s_nop 0
	global_load_lds_dwordx4 v132, s[26:27] offset:0
	global_load_lds_dwordx4 v133, s[26:27] offset:1024
	global_load_lds_dwordx4 v134, s[26:27] offset:2048
	global_load_lds_dwordx4 v135, s[26:27] offset:3072
	s_mov_b32 m0, s8
	s_nop 0
	global_load_lds_dwordx4 v132, s[28:29] offset:0
	global_load_lds_dwordx4 v133, s[28:29] offset:1024
	global_load_lds_dwordx4 v134, s[28:29] offset:2048
	global_load_lds_dwordx4 v135, s[28:29] offset:3072
	ds_read_b128 v[64:67], v136 offset:0
	ds_read_b128 v[96:99], v140 offset:0
	ds_read_b128 v[100:103], v140 offset:2048
	ds_read_b128 v[104:107], v140 offset:4096
	ds_read_b128 v[108:111], v140 offset:6144
	ds_read_b128 v[68:71], v136 offset:2048
	ds_read_b128 v[72:75], v136 offset:4096
	ds_read_b128 v[76:79], v136 offset:6144
	s_waitcnt lgkmcnt(3)
	v_mfma_f32_16x16x32_bf16 v[0:3], v[64:67], v[96:99], v[0:3]
	v_mfma_f32_16x16x32_bf16 v[4:7], v[64:67], v[100:103], v[4:7]
	ds_read_b128 v[80:83], v137 offset:0
	v_mfma_f32_16x16x32_bf16 v[8:11], v[64:67], v[104:107], v[8:11]
	v_mfma_f32_16x16x32_bf16 v[12:15], v[64:67], v[108:111], v[12:15]
	ds_read_b128 v[112:115], v141 offset:0
	s_waitcnt lgkmcnt(4)
	v_mfma_f32_16x16x32_bf16 v[16:19], v[68:71], v[96:99], v[16:19]
	v_mfma_f32_16x16x32_bf16 v[20:23], v[68:71], v[100:103], v[20:23]
	ds_read_b128 v[116:119], v141 offset:2048
	v_mfma_f32_16x16x32_bf16 v[24:27], v[68:71], v[104:107], v[24:27]
	v_mfma_f32_16x16x32_bf16 v[28:31], v[68:71], v[108:111], v[28:31]
	ds_read_b128 v[120:123], v141 offset:4096
	s_waitcnt lgkmcnt(5)
	v_mfma_f32_16x16x32_bf16 v[32:35], v[72:75], v[96:99], v[32:35]
	v_mfma_f32_16x16x32_bf16 v[36:39], v[72:75], v[100:103], v[36:39]
	ds_read_b128 v[124:127], v141 offset:6144
	v_mfma_f32_16x16x32_bf16 v[40:43], v[72:75], v[104:107], v[40:43]
	v_mfma_f32_16x16x32_bf16 v[44:47], v[72:75], v[108:111], v[44:47]
	ds_read_b128 v[84:87], v137 offset:2048
	s_waitcnt lgkmcnt(6)
	v_mfma_f32_16x16x32_bf16 v[48:51], v[76:79], v[96:99], v[48:51]
	v_mfma_f32_16x16x32_bf16 v[52:55], v[76:79], v[100:103], v[52:55]
	ds_read_b128 v[88:91], v137 offset:4096
	v_mfma_f32_16x16x32_bf16 v[56:59], v[76:79], v[104:107], v[56:59]
	v_mfma_f32_16x16x32_bf16 v[60:63], v[76:79], v[108:111], v[60:63]
	ds_read_b128 v[92:95], v137 offset:6144
	s_waitcnt lgkmcnt(3)
	v_mfma_f32_16x16x32_bf16 v[0:3], v[80:83], v[112:115], v[0:3]
	v_mfma_f32_16x16x32_bf16 v[4:7], v[80:83], v[116:119], v[4:7]
	v_mfma_f32_16x16x32_bf16 v[8:11], v[80:83], v[120:123], v[8:11]
	v_mfma_f32_16x16x32_bf16 v[12:15], v[80:83], v[124:127], v[12:15]
	s_waitcnt lgkmcnt(2)
	v_mfma_f32_16x16x32_bf16 v[16:19], v[84:87], v[112:115], v[16:19]
	v_mfma_f32_16x16x32_bf16 v[20:23], v[84:87], v[116:119], v[20:23]
	v_mfma_f32_16x16x32_bf16 v[24:27], v[84:87], v[120:123], v[24:27]
	v_mfma_f32_16x16x32_bf16 v[28:31], v[84:87], v[124:127], v[28:31]
	s_waitcnt lgkmcnt(1)
	v_mfma_f32_16x16x32_bf16 v[32:35], v[88:91], v[112:115], v[32:35]
	v_mfma_f32_16x16x32_bf16 v[36:39], v[88:91], v[116:119], v[36:39]
	v_mfma_f32_16x16x32_bf16 v[40:43], v[88:91], v[120:123], v[40:43]
	v_mfma_f32_16x16x32_bf16 v[44:47], v[88:91], v[124:127], v[44:47]
	s_waitcnt lgkmcnt(0)
	v_mfma_f32_16x16x32_bf16 v[48:51], v[92:95], v[112:115], v[48:51]
	v_mfma_f32_16x16x32_bf16 v[52:55], v[92:95], v[116:119], v[52:55]
	v_mfma_f32_16x16x32_bf16 v[56:59], v[92:95], v[120:123], v[56:59]
	v_mfma_f32_16x16x32_bf16 v[60:63], v[92:95], v[124:127], v[60:63]
	s_waitcnt vmcnt(0)
	s_barrier
	s_add_u32 s26, s26, 0x80
	s_addc_u32 s27, s27, 0
	s_add_u32 s28, s28, 0x80
	s_addc_u32 s29, s29, 0
	s_mov_b32 m0, s5
	s_nop 0
	global_load_lds_dwordx4 v132, s[26:27] offset:0
	global_load_lds_dwordx4 v133, s[26:27] offset:1024
	global_load_lds_dwordx4 v134, s[26:27] offset:2048
	global_load_lds_dwordx4 v135, s[26:27] offset:3072
	s_mov_b32 m0, s6
	s_nop 0
	global_load_lds_dwordx4 v132, s[28:29] offset:0
	global_load_lds_dwordx4 v133, s[28:29] offset:1024
	global_load_lds_dwordx4 v134, s[28:29] offset:2048
	global_load_lds_dwordx4 v135, s[28:29] offset:3072
	ds_read_b128 v[64:67], v138 offset:0
	ds_read_b128 v[96:99], v142 offset:0
	ds_read_b128 v[100:103], v142 offset:2048
	ds_read_b128 v[104:107], v142 offset:4096
	ds_read_b128 v[108:111], v142 offset:6144
	ds_read_b128 v[68:71], v138 offset:2048
	ds_read_b128 v[72:75], v138 offset:4096
	ds_read_b128 v[76:79], v138 offset:6144
	s_waitcnt lgkmcnt(3)
	v_mfma_f32_16x16x32_bf16 v[0:3], v[64:67], v[96:99], v[0:3]
	v_mfma_f32_16x16x32_bf16 v[4:7], v[64:67], v[100:103], v[4:7]
	ds_read_b128 v[80:83], v139 offset:0
	v_mfma_f32_16x16x32_bf16 v[8:11], v[64:67], v[104:107], v[8:11]
	v_mfma_f32_16x16x32_bf16 v[12:15], v[64:67], v[108:111], v[12:15]
	ds_read_b128 v[112:115], v143 offset:0
	s_waitcnt lgkmcnt(4)
	v_mfma_f32_16x16x32_bf16 v[16:19], v[68:71], v[96:99], v[16:19]
	v_mfma_f32_16x16x32_bf16 v[20:23], v[68:71], v[100:103], v[20:23]
	ds_read_b128 v[116:119], v143 offset:2048
	v_mfma_f32_16x16x32_bf16 v[24:27], v[68:71], v[104:107], v[24:27]
	v_mfma_f32_16x16x32_bf16 v[28:31], v[68:71], v[108:111], v[28:31]
	ds_read_b128 v[120:123], v143 offset:4096
	s_waitcnt lgkmcnt(5)
	v_mfma_f32_16x16x32_bf16 v[32:35], v[72:75], v[96:99], v[32:35]
	v_mfma_f32_16x16x32_bf16 v[36:39], v[72:75], v[100:103], v[36:39]
	ds_read_b128 v[124:127], v143 offset:6144
	v_mfma_f32_16x16x32_bf16 v[40:43], v[72:75], v[104:107], v[40:43]
	v_mfma_f32_16x16x32_bf16 v[44:47], v[72:75], v[108:111], v[44:47]
	ds_read_b128 v[84:87], v139 offset:2048
	s_waitcnt lgkmcnt(6)
	v_mfma_f32_16x16x32_bf16 v[48:51], v[76:79], v[96:99], v[48:51]
	v_mfma_f32_16x16x32_bf16 v[52:55], v[76:79], v[100:103], v[52:55]
	ds_read_b128 v[88:91], v139 offset:4096
	v_mfma_f32_16x16x32_bf16 v[56:59], v[76:79], v[104:107], v[56:59]
	v_mfma_f32_16x16x32_bf16 v[60:63], v[76:79], v[108:111], v[60:63]
	ds_read_b128 v[92:95], v139 offset:6144
	s_waitcnt lgkmcnt(3)
	v_mfma_f32_16x16x32_bf16 v[0:3], v[80:83], v[112:115], v[0:3]
	v_mfma_f32_16x16x32_bf16 v[4:7], v[80:83], v[116:119], v[4:7]
	v_mfma_f32_16x16x32_bf16 v[8:11], v[80:83], v[120:123], v[8:11]
	v_mfma_f32_16x16x32_bf16 v[12:15], v[80:83], v[124:127], v[12:15]
	s_waitcnt lgkmcnt(2)
	v_mfma_f32_16x16x32_bf16 v[16:19], v[84:87], v[112:115], v[16:19]
	v_mfma_f32_16x16x32_bf16 v[20:23], v[84:87], v[116:119], v[20:23]
	v_mfma_f32_16x16x32_bf16 v[24:27], v[84:87], v[120:123], v[24:27]
	v_mfma_f32_16x16x32_bf16 v[28:31], v[84:87], v[124:127], v[28:31]
	s_waitcnt lgkmcnt(1)
	v_mfma_f32_16x16x32_bf16 v[32:35], v[88:91], v[112:115], v[32:35]
	v_mfma_f32_16x16x32_bf16 v[36:39], v[88:91], v[116:119], v[36:39]
	v_mfma_f32_16x16x32_bf16 v[40:43], v[88:91], v[120:123], v[40:43]
	v_mfma_f32_16x16x32_bf16 v[44:47], v[88:91], v[124:127], v[44:47]
	s_waitcnt lgkmcnt(0)
	v_mfma_f32_16x16x32_bf16 v[48:51], v[92:95], v[112:115], v[48:51]
	v_mfma_f32_16x16x32_bf16 v[52:55], v[92:95], v[116:119], v[52:55]
	v_mfma_f32_16x16x32_bf16 v[56:59], v[92:95], v[120:123], v[56:59]
	v_mfma_f32_16x16x32_bf16 v[60:63], v[92:95], v[124:127], v[60:63]
	s_waitcnt vmcnt(0)
	s_barrier
	s_add_u32 s26, s26, 0x80
	s_addc_u32 s27, s27, 0
	s_add_u32 s28, s28, 0x80
	s_addc_u32 s29, s29, 0
	s_mov_b32 m0, s7
	s_nop 0
	global_load_lds_dwordx4 v132, s[26:27] offset:0
	global_load_lds_dwordx4 v133, s[26:27] offset:1024
	global_load_lds_dwordx4 v134, s[26:27] offset:2048
	global_load_lds_dwordx4 v135, s[26:27] offset:3072
	s_mov_b32 m0, s8
	s_nop 0
	global_load_lds_dwordx4 v132, s[28:29] offset:0
	global_load_lds_dwordx4 v133, s[28:29] offset:1024
	global_load_lds_dwordx4 v134, s[28:29] offset:2048
	global_load_lds_dwordx4 v135, s[28:29] offset:3072
	ds_read_b128 v[64:67], v136 offset:0
	ds_read_b128 v[96:99], v140 offset:0
	ds_read_b128 v[100:103], v140 offset:2048
	ds_read_b128 v[104:107], v140 offset:4096
	ds_read_b128 v[108:111], v140 offset:6144
	ds_read_b128 v[68:71], v136 offset:2048
	ds_read_b128 v[72:75], v136 offset:4096
	ds_read_b128 v[76:79], v136 offset:6144
	s_waitcnt lgkmcnt(3)
	v_mfma_f32_16x16x32_bf16 v[0:3], v[64:67], v[96:99], v[0:3]
	v_mfma_f32_16x16x32_bf16 v[4:7], v[64:67], v[100:103], v[4:7]
	ds_read_b128 v[80:83], v137 offset:0
	v_mfma_f32_16x16x32_bf16 v[8:11], v[64:67], v[104:107], v[8:11]
	v_mfma_f32_16x16x32_bf16 v[12:15], v[64:67], v[108:111], v[12:15]
	ds_read_b128 v[112:115], v141 offset:0
	s_waitcnt lgkmcnt(4)
	v_mfma_f32_16x16x32_bf16 v[16:19], v[68:71], v[96:99], v[16:19]
	v_mfma_f32_16x16x32_bf16 v[20:23], v[68:71], v[100:103], v[20:23]
	ds_read_b128 v[116:119], v141 offset:2048
	v_mfma_f32_16x16x32_bf16 v[24:27], v[68:71], v[104:107], v[24:27]
	v_mfma_f32_16x16x32_bf16 v[28:31], v[68:71], v[108:111], v[28:31]
	ds_read_b128 v[120:123], v141 offset:4096
	s_waitcnt lgkmcnt(5)
	v_mfma_f32_16x16x32_bf16 v[32:35], v[72:75], v[96:99], v[32:35]
	v_mfma_f32_16x16x32_bf16 v[36:39], v[72:75], v[100:103], v[36:39]
	ds_read_b128 v[124:127], v141 offset:6144
	v_mfma_f32_16x16x32_bf16 v[40:43], v[72:75], v[104:107], v[40:43]
	v_mfma_f32_16x16x32_bf16 v[44:47], v[72:75], v[108:111], v[44:47]
	ds_read_b128 v[84:87], v137 offset:2048
	s_waitcnt lgkmcnt(6)
	v_mfma_f32_16x16x32_bf16 v[48:51], v[76:79], v[96:99], v[48:51]
	v_mfma_f32_16x16x32_bf16 v[52:55], v[76:79], v[100:103], v[52:55]
	ds_read_b128 v[88:91], v137 offset:4096
	v_mfma_f32_16x16x32_bf16 v[56:59], v[76:79], v[104:107], v[56:59]
	v_mfma_f32_16x16x32_bf16 v[60:63], v[76:79], v[108:111], v[60:63]
	ds_read_b128 v[92:95], v137 offset:6144
	s_waitcnt lgkmcnt(3)
	v_mfma_f32_16x16x32_bf16 v[0:3], v[80:83], v[112:115], v[0:3]
	v_mfma_f32_16x16x32_bf16 v[4:7], v[80:83], v[116:119], v[4:7]
	v_mfma_f32_16x16x32_bf16 v[8:11], v[80:83], v[120:123], v[8:11]
	v_mfma_f32_16x16x32_bf16 v[12:15], v[80:83], v[124:127], v[12:15]
	s_waitcnt lgkmcnt(2)
	v_mfma_f32_16x16x32_bf16 v[16:19], v[84:87], v[112:115], v[16:19]
	v_mfma_f32_16x16x32_bf16 v[20:23], v[84:87], v[116:119], v[20:23]
	v_mfma_f32_16x16x32_bf16 v[24:27], v[84:87], v[120:123], v[24:27]
	v_mfma_f32_16x16x32_bf16 v[28:31], v[84:87], v[124:127], v[28:31]
	s_waitcnt lgkmcnt(1)
	v_mfma_f32_16x16x32_bf16 v[32:35], v[88:91], v[112:115], v[32:35]
	v_mfma_f32_16x16x32_bf16 v[36:39], v[88:91], v[116:119], v[36:39]
	v_mfma_f32_16x16x32_bf16 v[40:43], v[88:91], v[120:123], v[40:43]
	v_mfma_f32_16x16x32_bf16 v[44:47], v[88:91], v[124:127], v[44:47]
	s_waitcnt lgkmcnt(0)
	v_mfma_f32_16x16x32_bf16 v[48:51], v[92:95], v[112:115], v[48:51]
	v_mfma_f32_16x16x32_bf16 v[52:55], v[92:95], v[116:119], v[52:55]
	v_mfma_f32_16x16x32_bf16 v[56:59], v[92:95], v[120:123], v[56:59]
	v_mfma_f32_16x16x32_bf16 v[60:63], v[92:95], v[124:127], v[60:63]
	s_waitcnt vmcnt(0)
	s_barrier
	s_add_u32 s26, s26, 0x80
	s_addc_u32 s27, s27, 0
	s_add_u32 s28, s28, 0x80
	s_addc_u32 s29, s29, 0
	s_mov_b32 m0, s5
	s_nop 0
	global_load_lds_dwordx4 v132, s[26:27] offset:0
	global_load_lds_dwordx4 v133, s[26:27] offset:1024
	global_load_lds_dwordx4 v134, s[26:27] offset:2048
	global_load_lds_dwordx4 v135, s[26:27] offset:3072
	s_mov_b32 m0, s6
	s_nop 0
	global_load_lds_dwordx4 v132, s[28:29] offset:0
	global_load_lds_dwordx4 v133, s[28:29] offset:1024
	global_load_lds_dwordx4 v134, s[28:29] offset:2048
	global_load_lds_dwordx4 v135, s[28:29] offset:3072
	ds_read_b128 v[64:67], v138 offset:0
	ds_read_b128 v[96:99], v142 offset:0
	ds_read_b128 v[100:103], v142 offset:2048
	ds_read_b128 v[104:107], v142 offset:4096
	ds_read_b128 v[108:111], v142 offset:6144
	ds_read_b128 v[68:71], v138 offset:2048
	ds_read_b128 v[72:75], v138 offset:4096
	ds_read_b128 v[76:79], v138 offset:6144
	s_waitcnt lgkmcnt(3)
	v_mfma_f32_16x16x32_bf16 v[0:3], v[64:67], v[96:99], v[0:3]
	v_mfma_f32_16x16x32_bf16 v[4:7], v[64:67], v[100:103], v[4:7]
	ds_read_b128 v[80:83], v139 offset:0
	v_mfma_f32_16x16x32_bf16 v[8:11], v[64:67], v[104:107], v[8:11]
	v_mfma_f32_16x16x32_bf16 v[12:15], v[64:67], v[108:111], v[12:15]
	ds_read_b128 v[112:115], v143 offset:0
	s_waitcnt lgkmcnt(4)
	v_mfma_f32_16x16x32_bf16 v[16:19], v[68:71], v[96:99], v[16:19]
	v_mfma_f32_16x16x32_bf16 v[20:23], v[68:71], v[100:103], v[20:23]
	ds_read_b128 v[116:119], v143 offset:2048
	v_mfma_f32_16x16x32_bf16 v[24:27], v[68:71], v[104:107], v[24:27]
	v_mfma_f32_16x16x32_bf16 v[28:31], v[68:71], v[108:111], v[28:31]
	ds_read_b128 v[120:123], v143 offset:4096
	s_waitcnt lgkmcnt(5)
	v_mfma_f32_16x16x32_bf16 v[32:35], v[72:75], v[96:99], v[32:35]
	v_mfma_f32_16x16x32_bf16 v[36:39], v[72:75], v[100:103], v[36:39]
	ds_read_b128 v[124:127], v143 offset:6144
	v_mfma_f32_16x16x32_bf16 v[40:43], v[72:75], v[104:107], v[40:43]
	v_mfma_f32_16x16x32_bf16 v[44:47], v[72:75], v[108:111], v[44:47]
	ds_read_b128 v[84:87], v139 offset:2048
	s_waitcnt lgkmcnt(6)
	v_mfma_f32_16x16x32_bf16 v[48:51], v[76:79], v[96:99], v[48:51]
	v_mfma_f32_16x16x32_bf16 v[52:55], v[76:79], v[100:103], v[52:55]
	ds_read_b128 v[88:91], v139 offset:4096
	v_mfma_f32_16x16x32_bf16 v[56:59], v[76:79], v[104:107], v[56:59]
	v_mfma_f32_16x16x32_bf16 v[60:63], v[76:79], v[108:111], v[60:63]
	ds_read_b128 v[92:95], v139 offset:6144
	s_waitcnt lgkmcnt(3)
	v_mfma_f32_16x16x32_bf16 v[0:3], v[80:83], v[112:115], v[0:3]
	v_mfma_f32_16x16x32_bf16 v[4:7], v[80:83], v[116:119], v[4:7]
	v_mfma_f32_16x16x32_bf16 v[8:11], v[80:83], v[120:123], v[8:11]
	v_mfma_f32_16x16x32_bf16 v[12:15], v[80:83], v[124:127], v[12:15]
	s_waitcnt lgkmcnt(2)
	v_mfma_f32_16x16x32_bf16 v[16:19], v[84:87], v[112:115], v[16:19]
	v_mfma_f32_16x16x32_bf16 v[20:23], v[84:87], v[116:119], v[20:23]
	v_mfma_f32_16x16x32_bf16 v[24:27], v[84:87], v[120:123], v[24:27]
	v_mfma_f32_16x16x32_bf16 v[28:31], v[84:87], v[124:127], v[28:31]
	s_waitcnt lgkmcnt(1)
	v_mfma_f32_16x16x32_bf16 v[32:35], v[88:91], v[112:115], v[32:35]
	v_mfma_f32_16x16x32_bf16 v[36:39], v[88:91], v[116:119], v[36:39]
	v_mfma_f32_16x16x32_bf16 v[40:43], v[88:91], v[120:123], v[40:43]
	v_mfma_f32_16x16x32_bf16 v[44:47], v[88:91], v[124:127], v[44:47]
	s_waitcnt lgkmcnt(0)
	v_mfma_f32_16x16x32_bf16 v[48:51], v[92:95], v[112:115], v[48:51]
	v_mfma_f32_16x16x32_bf16 v[52:55], v[92:95], v[116:119], v[52:55]
	v_mfma_f32_16x16x32_bf16 v[56:59], v[92:95], v[120:123], v[56:59]
	v_mfma_f32_16x16x32_bf16 v[60:63], v[92:95], v[124:127], v[60:63]
	s_waitcnt vmcnt(0)
	s_barrier
	s_add_u32 s26, s26, 0x80
	s_addc_u32 s27, s27, 0
	s_add_u32 s28, s28, 0x80
	s_addc_u32 s29, s29, 0
	s_mov_b32 m0, s7
	s_nop 0
	global_load_lds_dwordx4 v132, s[26:27] offset:0
	global_load_lds_dwordx4 v133, s[26:27] offset:1024
	global_load_lds_dwordx4 v134, s[26:27] offset:2048
	global_load_lds_dwordx4 v135, s[26:27] offset:3072
	s_mov_b32 m0, s8
	s_nop 0
	global_load_lds_dwordx4 v132, s[28:29] offset:0
	global_load_lds_dwordx4 v133, s[28:29] offset:1024
	global_load_lds_dwordx4 v134, s[28:29] offset:2048
	global_load_lds_dwordx4 v135, s[28:29] offset:3072
	ds_read_b128 v[64:67], v136 offset:0
	ds_read_b128 v[96:99], v140 offset:0
	ds_read_b128 v[100:103], v140 offset:2048
	ds_read_b128 v[104:107], v140 offset:4096
	ds_read_b128 v[108:111], v140 offset:6144
	ds_read_b128 v[68:71], v136 offset:2048
	ds_read_b128 v[72:75], v136 offset:4096
	ds_read_b128 v[76:79], v136 offset:6144
	s_waitcnt lgkmcnt(3)
	v_mfma_f32_16x16x32_bf16 v[0:3], v[64:67], v[96:99], v[0:3]
	v_mfma_f32_16x16x32_bf16 v[4:7], v[64:67], v[100:103], v[4:7]
	ds_read_b128 v[80:83], v137 offset:0
	v_mfma_f32_16x16x32_bf16 v[8:11], v[64:67], v[104:107], v[8:11]
	v_mfma_f32_16x16x32_bf16 v[12:15], v[64:67], v[108:111], v[12:15]
	ds_read_b128 v[112:115], v141 offset:0
	s_waitcnt lgkmcnt(4)
	v_mfma_f32_16x16x32_bf16 v[16:19], v[68:71], v[96:99], v[16:19]
	v_mfma_f32_16x16x32_bf16 v[20:23], v[68:71], v[100:103], v[20:23]
	ds_read_b128 v[116:119], v141 offset:2048
	v_mfma_f32_16x16x32_bf16 v[24:27], v[68:71], v[104:107], v[24:27]
	v_mfma_f32_16x16x32_bf16 v[28:31], v[68:71], v[108:111], v[28:31]
	ds_read_b128 v[120:123], v141 offset:4096
	s_waitcnt lgkmcnt(5)
	v_mfma_f32_16x16x32_bf16 v[32:35], v[72:75], v[96:99], v[32:35]
	v_mfma_f32_16x16x32_bf16 v[36:39], v[72:75], v[100:103], v[36:39]
	ds_read_b128 v[124:127], v141 offset:6144
	v_mfma_f32_16x16x32_bf16 v[40:43], v[72:75], v[104:107], v[40:43]
	v_mfma_f32_16x16x32_bf16 v[44:47], v[72:75], v[108:111], v[44:47]
	ds_read_b128 v[84:87], v137 offset:2048
	s_waitcnt lgkmcnt(6)
	v_mfma_f32_16x16x32_bf16 v[48:51], v[76:79], v[96:99], v[48:51]
	v_mfma_f32_16x16x32_bf16 v[52:55], v[76:79], v[100:103], v[52:55]
	ds_read_b128 v[88:91], v137 offset:4096
	v_mfma_f32_16x16x32_bf16 v[56:59], v[76:79], v[104:107], v[56:59]
	v_mfma_f32_16x16x32_bf16 v[60:63], v[76:79], v[108:111], v[60:63]
	ds_read_b128 v[92:95], v137 offset:6144
	s_waitcnt lgkmcnt(3)
	v_mfma_f32_16x16x32_bf16 v[0:3], v[80:83], v[112:115], v[0:3]
	v_mfma_f32_16x16x32_bf16 v[4:7], v[80:83], v[116:119], v[4:7]
	v_mfma_f32_16x16x32_bf16 v[8:11], v[80:83], v[120:123], v[8:11]
	v_mfma_f32_16x16x32_bf16 v[12:15], v[80:83], v[124:127], v[12:15]
	s_waitcnt lgkmcnt(2)
	v_mfma_f32_16x16x32_bf16 v[16:19], v[84:87], v[112:115], v[16:19]
	v_mfma_f32_16x16x32_bf16 v[20:23], v[84:87], v[116:119], v[20:23]
	v_mfma_f32_16x16x32_bf16 v[24:27], v[84:87], v[120:123], v[24:27]
	v_mfma_f32_16x16x32_bf16 v[28:31], v[84:87], v[124:127], v[28:31]
	s_waitcnt lgkmcnt(1)
	v_mfma_f32_16x16x32_bf16 v[32:35], v[88:91], v[112:115], v[32:35]
	v_mfma_f32_16x16x32_bf16 v[36:39], v[88:91], v[116:119], v[36:39]
	v_mfma_f32_16x16x32_bf16 v[40:43], v[88:91], v[120:123], v[40:43]
	v_mfma_f32_16x16x32_bf16 v[44:47], v[88:91], v[124:127], v[44:47]
	s_waitcnt lgkmcnt(0)
	v_mfma_f32_16x16x32_bf16 v[48:51], v[92:95], v[112:115], v[48:51]
	v_mfma_f32_16x16x32_bf16 v[52:55], v[92:95], v[116:119], v[52:55]
	v_mfma_f32_16x16x32_bf16 v[56:59], v[92:95], v[120:123], v[56:59]
	v_mfma_f32_16x16x32_bf16 v[60:63], v[92:95], v[124:127], v[60:63]
	s_waitcnt vmcnt(0)
	s_barrier
	ds_read_b128 v[64:67], v138 offset:0
	ds_read_b128 v[96:99], v142 offset:0
	ds_read_b128 v[100:103], v142 offset:2048
	ds_read_b128 v[104:107], v142 offset:4096
	ds_read_b128 v[108:111], v142 offset:6144
	ds_read_b128 v[68:71], v138 offset:2048
	ds_read_b128 v[72:75], v138 offset:4096
	ds_read_b128 v[76:79], v138 offset:6144
	s_waitcnt lgkmcnt(3)
	v_mfma_f32_16x16x32_bf16 v[0:3], v[64:67], v[96:99], v[0:3]
	v_mfma_f32_16x16x32_bf16 v[4:7], v[64:67], v[100:103], v[4:7]
	ds_read_b128 v[80:83], v139 offset:0
	v_mfma_f32_16x16x32_bf16 v[8:11], v[64:67], v[104:107], v[8:11]
	v_mfma_f32_16x16x32_bf16 v[12:15], v[64:67], v[108:111], v[12:15]
	ds_read_b128 v[112:115], v143 offset:0
	s_waitcnt lgkmcnt(4)
	v_mfma_f32_16x16x32_bf16 v[16:19], v[68:71], v[96:99], v[16:19]
	v_mfma_f32_16x16x32_bf16 v[20:23], v[68:71], v[100:103], v[20:23]
	ds_read_b128 v[116:119], v143 offset:2048
	v_mfma_f32_16x16x32_bf16 v[24:27], v[68:71], v[104:107], v[24:27]
	v_mfma_f32_16x16x32_bf16 v[28:31], v[68:71], v[108:111], v[28:31]
	ds_read_b128 v[120:123], v143 offset:4096
	s_waitcnt lgkmcnt(5)
	v_mfma_f32_16x16x32_bf16 v[32:35], v[72:75], v[96:99], v[32:35]
	v_mfma_f32_16x16x32_bf16 v[36:39], v[72:75], v[100:103], v[36:39]
	ds_read_b128 v[124:127], v143 offset:6144
	v_mfma_f32_16x16x32_bf16 v[40:43], v[72:75], v[104:107], v[40:43]
	v_mfma_f32_16x16x32_bf16 v[44:47], v[72:75], v[108:111], v[44:47]
	ds_read_b128 v[84:87], v139 offset:2048
	s_waitcnt lgkmcnt(6)
	v_mfma_f32_16x16x32_bf16 v[48:51], v[76:79], v[96:99], v[48:51]
	v_mfma_f32_16x16x32_bf16 v[52:55], v[76:79], v[100:103], v[52:55]
	ds_read_b128 v[88:91], v139 offset:4096
	v_mfma_f32_16x16x32_bf16 v[56:59], v[76:79], v[104:107], v[56:59]
	v_mfma_f32_16x16x32_bf16 v[60:63], v[76:79], v[108:111], v[60:63]
	ds_read_b128 v[92:95], v139 offset:6144
	s_waitcnt lgkmcnt(3)
	v_mfma_f32_16x16x32_bf16 v[0:3], v[80:83], v[112:115], v[0:3]
	v_mfma_f32_16x16x32_bf16 v[4:7], v[80:83], v[116:119], v[4:7]
	v_mfma_f32_16x16x32_bf16 v[8:11], v[80:83], v[120:123], v[8:11]
	v_mfma_f32_16x16x32_bf16 v[12:15], v[80:83], v[124:127], v[12:15]
	s_waitcnt lgkmcnt(2)
	v_mfma_f32_16x16x32_bf16 v[16:19], v[84:87], v[112:115], v[16:19]
	v_mfma_f32_16x16x32_bf16 v[20:23], v[84:87], v[116:119], v[20:23]
	v_mfma_f32_16x16x32_bf16 v[24:27], v[84:87], v[120:123], v[24:27]
	v_mfma_f32_16x16x32_bf16 v[28:31], v[84:87], v[124:127], v[28:31]
	s_waitcnt lgkmcnt(1)
	v_mfma_f32_16x16x32_bf16 v[32:35], v[88:91], v[112:115], v[32:35]
	v_mfma_f32_16x16x32_bf16 v[36:39], v[88:91], v[116:119], v[36:39]
	v_mfma_f32_16x16x32_bf16 v[40:43], v[88:91], v[120:123], v[40:43]
	v_mfma_f32_16x16x32_bf16 v[44:47], v[88:91], v[124:127], v[44:47]
	s_waitcnt lgkmcnt(0)
	v_mfma_f32_16x16x32_bf16 v[48:51], v[92:95], v[112:115], v[48:51]
	v_mfma_f32_16x16x32_bf16 v[52:55], v[92:95], v[116:119], v[52:55]
	v_mfma_f32_16x16x32_bf16 v[56:59], v[92:95], v[120:123], v[56:59]
	v_mfma_f32_16x16x32_bf16 v[60:63], v[92:95], v[124:127], v[60:63]
	v_readlane_b32 s38, v255, 35
	s_add_i32 s38, s25, s38
	s_cmpk_lt_u32 s38, 0x1280
	s_cbranch_scc0 .Lgin_nonext
	s_and_b32 s0, s38, 63
	s_lshr_b32 s1, s38, 6
	s_mul_i32 s4, s70, 0x1280000
	s_lshl_b32 s39, s1, 18
	s_add_u32 s4, s4, s39
	s_add_u32 s26, s96, s4
	s_addc_u32 s27, s97, 0
	s_lshl_b32 s4, s0, 18
	s_add_u32 s4, s4, 0x82a6100
	s_add_u32 s28, s96, s4
	s_addc_u32 s29, s97, 0
	s_mov_b32 m0, s5
	s_nop 0
	global_load_lds_dwordx4 v132, s[26:27] offset:0
	global_load_lds_dwordx4 v133, s[26:27] offset:1024
	global_load_lds_dwordx4 v134, s[26:27] offset:2048
	global_load_lds_dwordx4 v135, s[26:27] offset:3072
	s_mov_b32 m0, s6
	s_nop 0
	global_load_lds_dwordx4 v132, s[28:29] offset:0
	global_load_lds_dwordx4 v133, s[28:29] offset:1024
	global_load_lds_dwordx4 v134, s[28:29] offset:2048
	global_load_lds_dwordx4 v135, s[28:29] offset:3072
.Lgin_nonext:
	s_and_b32 s0, s25, 63
	s_lshr_b32 s1, s25, 6
	s_mul_i32 s4, s0, 0x250000
	s_lshl_b32 s39, s1, 8
	s_add_u32 s4, s4, s39
	s_add_u32 s4, s4, 0x92a6100
	s_add_u32 s36, s96, s4
	s_addc_u32 s37, s97, 0
	s_nop 7
	v_cvt_pk_bf16_f32 v0, v0, v1
	v_cvt_pk_bf16_f32 v1, v2, v3
	global_store_dwordx2 v146, v[0:1], s[36:37] offset:0
	v_cvt_pk_bf16_f32 v16, v16, v17
	v_cvt_pk_bf16_f32 v17, v18, v19
	global_store_dwordx2 v146, v[16:17], s[36:37] offset:32
	v_cvt_pk_bf16_f32 v32, v32, v33
	v_cvt_pk_bf16_f32 v33, v34, v35
	global_store_dwordx2 v146, v[32:33], s[36:37] offset:64
	v_cvt_pk_bf16_f32 v48, v48, v49
	v_cvt_pk_bf16_f32 v49, v50, v51
	global_store_dwordx2 v146, v[48:49], s[36:37] offset:96
	v_cvt_pk_bf16_f32 v4, v4, v5
	v_cvt_pk_bf16_f32 v5, v6, v7
	global_store_dwordx2 v147, v[4:5], s[36:37] offset:0
	v_cvt_pk_bf16_f32 v20, v20, v21
	v_cvt_pk_bf16_f32 v21, v22, v23
	global_store_dwordx2 v147, v[20:21], s[36:37] offset:32
	v_cvt_pk_bf16_f32 v36, v36, v37
	v_cvt_pk_bf16_f32 v37, v38, v39
	global_store_dwordx2 v147, v[36:37], s[36:37] offset:64
	v_cvt_pk_bf16_f32 v52, v52, v53
	v_cvt_pk_bf16_f32 v53, v54, v55
	global_store_dwordx2 v147, v[52:53], s[36:37] offset:96
	v_cvt_pk_bf16_f32 v8, v8, v9
	v_cvt_pk_bf16_f32 v9, v10, v11
	global_store_dwordx2 v148, v[8:9], s[36:37] offset:0
	v_cvt_pk_bf16_f32 v24, v24, v25
	v_cvt_pk_bf16_f32 v25, v26, v27
	global_store_dwordx2 v148, v[24:25], s[36:37] offset:32
	v_cvt_pk_bf16_f32 v40, v40, v41
	v_cvt_pk_bf16_f32 v41, v42, v43
	global_store_dwordx2 v148, v[40:41], s[36:37] offset:64
	v_cvt_pk_bf16_f32 v56, v56, v57
	v_cvt_pk_bf16_f32 v57, v58, v59
	global_store_dwordx2 v148, v[56:57], s[36:37] offset:96
	v_cvt_pk_bf16_f32 v12, v12, v13
	v_cvt_pk_bf16_f32 v13, v14, v15
	global_store_dwordx2 v149, v[12:13], s[36:37] offset:0
	v_cvt_pk_bf16_f32 v28, v28, v29
	v_cvt_pk_bf16_f32 v29, v30, v31
	global_store_dwordx2 v149, v[28:29], s[36:37] offset:32
	v_cvt_pk_bf16_f32 v44, v44, v45
	v_cvt_pk_bf16_f32 v45, v46, v47
	global_store_dwordx2 v149, v[44:45], s[36:37] offset:64
	v_cvt_pk_bf16_f32 v60, v60, v61
	v_cvt_pk_bf16_f32 v61, v62, v63
	global_store_dwordx2 v149, v[60:61], s[36:37] offset:96
	s_mov_b32 s25, s38
	s_cmpk_lt_u32 s25, 0x1280
	s_cbranch_scc1 .Lgin_tile
	v_readlane_b32 s36, v255, 33
	v_readlane_b32 s37, v255, 34
	v_readlane_b32 s38, v255, 35
	v_readlane_b32 s39, v255, 36

	.amdhsa_kernel _Z14fwd_megakernel6Paramsii
		.amdhsa_group_segment_fixed_size 77824
		.amdhsa_private_segment_fixed_size 0
		.amdhsa_kernarg_size 592
		.amdhsa_user_sgpr_count 2
		.amdhsa_user_sgpr_dispatch_ptr 0
		.amdhsa_user_sgpr_queue_ptr 0
		.amdhsa_user_sgpr_kernarg_segment_ptr 1
		.amdhsa_user_sgpr_dispatch_id 0
		.amdhsa_user_sgpr_kernarg_preload_length 0
		.amdhsa_user_sgpr_kernarg_preload_offset 0
		.amdhsa_user_sgpr_private_segment_size 0
		.amdhsa_uses_dynamic_stack 0
		.amdhsa_enable_private_segment 0
		.amdhsa_system_sgpr_workgroup_id_x 1
		.amdhsa_system_sgpr_workgroup_id_y 0
		.amdhsa_system_sgpr_workgroup_id_z 0
		.amdhsa_system_sgpr_workgroup_info 0
		.amdhsa_system_vgpr_workitem_id 2
		.amdhsa_next_free_vgpr 256
		.amdhsa_next_free_sgpr 98
		.amdhsa_accum_offset 256
		.amdhsa_reserve_vcc 1
		.amdhsa_float_round_mode_32 0
		.amdhsa_float_round_mode_16_64 0
		.amdhsa_float_denorm_mode_32 3
		.amdhsa_float_denorm_mode_16_64 3
		.amdhsa_dx10_clamp 1
		.amdhsa_ieee_mode 1
		.amdhsa_fp16_overflow 0
		.amdhsa_tg_split 0
		.amdhsa_exception_fp_ieee_invalid_op 0
		.amdhsa_exception_fp_denorm_src 0
		.amdhsa_exception_fp_ieee_div_zero 0
		.amdhsa_exception_fp_ieee_overflow 0
		.amdhsa_exception_fp_ieee_underflow 0
		.amdhsa_exception_fp_ieee_inexact 0
		.amdhsa_exception_int_div_zero 0
	.end_amdhsa_kernel

amdhsa.kernels:
  - .agpr_count:     0
    .args:
      - .offset:         0
        .size:           328
        .value_kind:     by_value
      - .offset:         328
        .size:           4
        .value_kind:     by_value
      - .offset:         332
        .size:           4
        .value_kind:     by_value
      - .offset:         336
        .size:           4
        .value_kind:     hidden_block_count_x
      - .offset:         340
        .size:           4
        .value_kind:     hidden_block_count_y
      - .offset:         344
        .size:           4
        .value_kind:     hidden_block_count_z
      - .offset:         348
        .size:           2
        .value_kind:     hidden_group_size_x
      - .offset:         350
        .size:           2
        .value_kind:     hidden_group_size_y
      - .offset:         352
        .size:           2
        .value_kind:     hidden_group_size_z
      - .offset:         354
        .size:           2
        .value_kind:     hidden_remainder_x
      - .offset:         356
        .size:           2
        .value_kind:     hidden_remainder_y
      - .offset:         358
        .size:           2
        .value_kind:     hidden_remainder_z
      - .offset:         376
        .size:           8
        .value_kind:     hidden_global_offset_x
      - .offset:         384
        .size:           8
        .value_kind:     hidden_global_offset_y
      - .offset:         392
        .size:           8
        .value_kind:     hidden_global_offset_z
      - .offset:         400
        .size:           2
        .value_kind:     hidden_grid_dims
      - .offset:         424
        .size:           8
        .value_kind:     hidden_multigrid_sync_arg
    .group_segment_fixed_size: 77824
    .kernarg_segment_align: 8
    .kernarg_segment_size: 592
    .language:       OpenCL C
    .language_version:
      - 2
      - 0
    .max_flat_workgroup_size: 256
    .name:           _Z14fwd_megakernel6Paramsii
    .private_segment_fixed_size: 0
    .sgpr_count:     104
    .sgpr_spill_count: 253
    .symbol:         _Z14fwd_megakernel6Paramsii.kd
    .uniform_work_group_size: 1
    .uses_dynamic_stack: false
    .vgpr_count:     256
    .vgpr_spill_count: 0
    .wavefront_size: 64
